# R1 + C1: software bf16 RNE packs (bfe/add3/lshr/and_or, 6 VALU) in norm/prologue/weight-tail replaced by v_cvt_pk_bf16_f32 (same RNE result), 181 sites
# speedup vs baseline: 1.0111x; 1.0010x over previous
.LBB0_40:
	s_mul_i32 s0, s16, 0x5000000
	s_add_u32 s18, s10, s0
	s_addc_u32 s19, s11, 0
	s_lshl_b32 s0, s64, 6
	v_or_b32_e32 v58, s0, v7
	v_ashrrev_i32_e32 v5, 31, v4
	v_lshl_add_u64 v[4:5], v[4:5], 2, s[18:19]
	v_or_b32_e32 v32, 8, v58
	v_or_b32_e32 v38, 16, v58
	v_or_b32_e32 v40, 24, v58
	v_or_b32_e32 v46, 32, v58
	v_or_b32_e32 v48, 40, v58
	v_mad_i64_i32 v[30:31], s[18:19], v58, s61, v[4:5]
	v_mad_i64_i32 v[34:35], s[18:19], v32, s61, v[4:5]
	v_mad_i64_i32 v[38:39], s[18:19], v38, s61, v[4:5]
	v_mad_i64_i32 v[42:43], s[18:19], v40, s61, v[4:5]
	v_mad_i64_i32 v[46:47], s[18:19], v46, s61, v[4:5]
	v_mad_i64_i32 v[50:51], s[18:19], v48, s61, v[4:5]
	global_load_dwordx4 v[30:33], v[30:31], off
	s_nop 0
	global_load_dwordx4 v[34:37], v[34:35], off
	s_nop 0
	global_load_dwordx4 v[38:41], v[38:39], off
	s_nop 0
	global_load_dwordx4 v[42:45], v[42:43], off
	s_nop 0
	global_load_dwordx4 v[46:49], v[46:47], off
	s_nop 0
	global_load_dwordx4 v[50:53], v[50:51], off
	v_or_b32_e32 v54, 48, v58
	v_mad_i64_i32 v[54:55], s[18:19], v54, s61, v[4:5]
	global_load_dwordx4 v[54:57], v[54:55], off
	v_or_b32_e32 v58, 56, v58
	v_mad_i64_i32 v[4:5], s[18:19], v58, s61, v[4:5]
	global_load_dwordx4 v[58:61], v[4:5], off
	s_ashr_i32 s1, s0, 31
	s_lshl_b64 s[0:1], s[0:1], 1
	v_or_b32_e32 v4, s63, v7
	s_add_u32 s0, s17, s0
	v_ashrrev_i32_e32 v5, 31, v4
	s_addc_u32 s1, s62, s1
	v_lshlrev_b64 v[4:5], 12, v[4:5]
	v_lshl_add_u64 v[62:63], s[0:1], 0, v[2:3]
	v_lshl_add_u64 v[4:5], v[62:63], 0, v[4:5]
	s_waitcnt vmcnt(7)
	ds_write2_b32 v14, v30, v31 offset1:1
	ds_write2_b32 v14, v32, v33 offset0:2 offset1:3
	s_waitcnt vmcnt(6)
	ds_write2_b32 v15, v34, v35 offset1:1
	ds_write2_b32 v16, v36, v37 offset1:1
	s_waitcnt vmcnt(5)
	ds_write2_b32 v17, v38, v39 offset1:1
	ds_write2_b32 v18, v40, v41 offset1:1
	s_waitcnt vmcnt(4)
	ds_write2_b32 v19, v42, v43 offset1:1
	ds_write2_b32 v20, v44, v45 offset1:1
	s_waitcnt vmcnt(3)
	ds_write2_b32 v21, v46, v47 offset1:1
	ds_write2_b32 v22, v48, v49 offset1:1
	s_waitcnt vmcnt(2)
	ds_write2_b32 v23, v50, v51 offset1:1
	ds_write2_b32 v24, v52, v53 offset1:1
	s_waitcnt vmcnt(1)
	ds_write2_b32 v25, v54, v55 offset1:1
	ds_write2_b32 v26, v56, v57 offset1:1
	s_waitcnt vmcnt(0)
	ds_write2_b32 v27, v58, v59 offset1:1
	ds_write2_b32 v28, v60, v61 offset1:1
	s_waitcnt lgkmcnt(0)
	ds_read2_b32 v[34:35], v11 offset0:33 offset1:41
	ds_read2_b32 v[36:37], v11 offset1:8
	ds_read2_b32 v[38:39], v11 offset0:66 offset1:74
	ds_read2_b32 v[40:41], v11 offset0:99 offset1:107
	ds_read2_b32 v[42:43], v11 offset0:132 offset1:140
	ds_read2_b32 v[44:45], v11 offset0:165 offset1:173
	ds_read2_b32 v[46:47], v11 offset0:198 offset1:206
	ds_read2_b32 v[48:49], v11 offset0:231 offset1:239
	s_waitcnt lgkmcnt(6)
	v_bfe_u32 v30, v36, 16, 1
	v_bfe_u32 v31, v34, 16, 1
	s_waitcnt lgkmcnt(5)
	v_bfe_u32 v32, v38, 16, 1
	s_waitcnt lgkmcnt(3)
	v_bfe_u32 v50, v42, 16, 1
	s_waitcnt lgkmcnt(1)
	v_bfe_u32 v52, v46, 16, 1
	v_bfe_u32 v33, v40, 16, 1
	v_bfe_u32 v51, v44, 16, 1
	s_waitcnt lgkmcnt(0)
	v_bfe_u32 v53, v48, 16, 1
	v_add3_u32 v30, v36, v30, s46
	v_add3_u32 v31, v34, v31, s46
	v_add3_u32 v32, v38, v32, s46
	v_add3_u32 v34, v42, v50, s46
	v_add3_u32 v38, v46, v52, s46
	v_add3_u32 v33, v40, v33, s46
	v_add3_u32 v36, v44, v51, s46
	v_add3_u32 v40, v48, v53, s46
	v_lshrrev_b32_e32 v30, 16, v30
	v_lshrrev_b32_e32 v32, 16, v32
	v_lshrrev_b32_e32 v34, 16, v34
	v_lshrrev_b32_e32 v38, 16, v38
	v_bfe_u32 v54, v37, 16, 1
	v_and_or_b32 v30, v31, s47, v30
	v_and_or_b32 v31, v33, s47, v32
	v_and_or_b32 v32, v36, s47, v34
	v_and_or_b32 v33, v40, s47, v38
	global_store_dwordx4 v[4:5], v[30:33], off
	v_add3_u32 v4, v37, v54, s46
	v_bfe_u32 v5, v35, 16, 1
	v_lshrrev_b32_e32 v4, 16, v4
	v_add3_u32 v5, v35, v5, s46
	v_and_or_b32 v30, v5, s47, v4
	v_cvt_pk_bf16_f32 v31, v39, v41
	v_cvt_pk_bf16_f32 v32, v43, v45
	v_cvt_pk_bf16_f32 v33, v47, v49
	v_or_b32_e32 v4, s63, v8
	v_ashrrev_i32_e32 v5, 31, v4
	v_lshlrev_b64 v[4:5], 12, v[4:5]
	ds_read2_b32 v[34:35], v11 offset0:16 offset1:24
	v_lshl_add_u64 v[4:5], v[62:63], 0, v[4:5]
	global_store_dwordx4 v[4:5], v[30:33], off
	ds_read2_b32 v[4:5], v11 offset0:49 offset1:57
	ds_read2_b32 v[36:37], v11 offset0:82 offset1:90
	ds_read2_b32 v[38:39], v11 offset0:115 offset1:123
	s_waitcnt lgkmcnt(3)
	v_bfe_u32 v30, v34, 16, 1
	v_add3_u32 v30, v34, v30, s46
	s_waitcnt lgkmcnt(2)
	v_bfe_u32 v31, v4, 16, 1
	ds_read2_b32 v[40:41], v11 offset0:148 offset1:156
	v_lshrrev_b32_e32 v30, 16, v30
	v_add3_u32 v4, v4, v31, s46
	ds_read2_b32 v[42:43], v11 offset0:181 offset1:189
	v_and_or_b32 v30, v4, s47, v30
	s_waitcnt lgkmcnt(3)
	s_waitcnt lgkmcnt(2)
	ds_read2_b32 v[44:45], v11 offset0:214 offset1:222
	ds_read2_b32 v[46:47], v11 offset0:247 offset1:255
	v_cvt_pk_bf16_f32 v31, v36, v38
	s_waitcnt lgkmcnt(3)
	s_waitcnt lgkmcnt(2)
	v_cvt_pk_bf16_f32 v32, v40, v42
	s_waitcnt lgkmcnt(1)
	v_or_b32_e32 v48, s63, v9
	s_waitcnt lgkmcnt(0)
	v_ashrrev_i32_e32 v49, 31, v48
	v_lshlrev_b64 v[48:49], 12, v[48:49]
	v_cvt_pk_bf16_f32 v33, v44, v46
	v_lshl_add_u64 v[48:49], v[62:63], 0, v[48:49]
	v_bfe_u32 v4, v35, 16, 1
	global_store_dwordx4 v[48:49], v[30:33], off
	v_add3_u32 v4, v35, v4, s46
	v_lshrrev_b32_e32 v4, 16, v4
	v_bfe_u32 v30, v5, 16, 1
	v_add3_u32 v5, v5, v30, s46
	v_and_or_b32 v30, v5, s47, v4
	v_cvt_pk_bf16_f32 v31, v37, v39
	v_cvt_pk_bf16_f32 v32, v41, v43
	v_cvt_pk_bf16_f32 v33, v45, v47
	v_or_b32_e32 v4, s63, v10
	v_ashrrev_i32_e32 v5, 31, v4
	v_lshlrev_b64 v[4:5], 12, v[4:5]
	v_lshl_add_u64 v[4:5], v[62:63], 0, v[4:5]
	global_store_dwordx4 v[4:5], v[30:33], off
	s_waitcnt lgkmcnt(0)

.LBB0_46:
	s_cmpk_gt_u32 s18, 0x2bff
	s_cbranch_scc0 .LBB0_60
	s_cmpk_gt_u32 s18, 0x33ff
	s_cbranch_scc0 .LBB0_57
	s_cmpk_gt_u32 s18, 0x3bff
	s_cbranch_scc0 .LBB0_54
	s_cmpk_gt_u32 s18, 0x67ff
	s_mul_i32 s19, s16, 0x2c00000
	s_cbranch_scc0 .LBB0_51
	s_add_u32 s64, s34, s19
	s_addc_u32 s65, s35, 0
	s_lshl_b32 s0, s18, 5
	s_and_b32 s0, s0, 0x7e0
	s_add_i32 s1, s18, 0x9800
	v_or_b32_e32 v4, s0, v6
	s_and_b32 s1, s1, 0xffc0
	v_or_b32_e32 v30, s1, v7
	v_lshlrev_b32_e32 v4, 2, v4
	v_mov_b32_e32 v5, v3
	v_lshl_add_u64 v[4:5], s[64:65], 0, v[4:5]
	v_lshlrev_b32_e32 v30, 13, v30
	v_mov_b32_e32 v31, v3
	v_lshl_add_u64 v[4:5], v[4:5], 0, v[30:31]
	v_add_co_u32_e32 v34, vcc, s38, v4
	s_lshl_b32 s1, s1, 1
	s_nop 0
	v_addc_co_u32_e32 v35, vcc, 0, v5, vcc
	v_add_co_u32_e32 v38, vcc, s39, v4
	global_load_dwordx4 v[30:33], v[4:5], off
	s_nop 0
	global_load_dwordx4 v[34:37], v[34:35], off
	v_addc_co_u32_e32 v39, vcc, 0, v5, vcc
	v_add_co_u32_e32 v42, vcc, s41, v4
	s_add_u32 s64, s17, s1
	s_nop 0
	v_addc_co_u32_e32 v43, vcc, 0, v5, vcc
	v_add_co_u32_e32 v46, vcc, s42, v4
	global_load_dwordx4 v[38:41], v[38:39], off
	s_nop 0
	global_load_dwordx4 v[42:45], v[42:43], off
	v_addc_co_u32_e32 v47, vcc, 0, v5, vcc
	v_add_co_u32_e32 v50, vcc, s43, v4
	s_addc_u32 s65, s62, 0
	s_nop 0
	v_addc_co_u32_e32 v51, vcc, 0, v5, vcc
	global_load_dwordx4 v[46:49], v[46:47], off
	s_nop 0
	global_load_dwordx4 v[50:53], v[50:51], off
	v_add_co_u32_e32 v54, vcc, s44, v4
	s_nop 1
	v_addc_co_u32_e32 v55, vcc, 0, v5, vcc
	global_load_dwordx4 v[54:57], v[54:55], off
	v_add_co_u32_e32 v4, vcc, s45, v4
	s_nop 1
	v_addc_co_u32_e32 v5, vcc, 0, v5, vcc
	global_load_dwordx4 v[58:61], v[4:5], off
	v_lshl_add_u64 v[4:5], s[64:65], 0, v[2:3]
	v_lshl_add_u64 v[4:5], v[4:5], 0, s[4:5]
	s_waitcnt vmcnt(7)
	ds_write2_b32 v14, v30, v31 offset1:1
	ds_write2_b32 v14, v32, v33 offset0:2 offset1:3
	s_waitcnt vmcnt(6)
	ds_write2_b32 v15, v34, v35 offset1:1
	ds_write2_b32 v16, v36, v37 offset1:1
	s_waitcnt vmcnt(5)
	ds_write2_b32 v17, v38, v39 offset1:1
	ds_write2_b32 v18, v40, v41 offset1:1
	s_waitcnt vmcnt(4)
	ds_write2_b32 v19, v42, v43 offset1:1
	ds_write2_b32 v20, v44, v45 offset1:1
	s_waitcnt vmcnt(3)
	ds_write2_b32 v21, v46, v47 offset1:1
	ds_write2_b32 v22, v48, v49 offset1:1
	s_waitcnt vmcnt(2)
	ds_write2_b32 v23, v50, v51 offset1:1
	ds_write2_b32 v24, v52, v53 offset1:1
	s_waitcnt vmcnt(1)
	ds_write2_b32 v25, v54, v55 offset1:1
	ds_write2_b32 v26, v56, v57 offset1:1
	s_waitcnt vmcnt(0)
	ds_write2_b32 v27, v58, v59 offset1:1
	ds_write2_b32 v28, v60, v61 offset1:1
	s_waitcnt lgkmcnt(0)
	ds_read2_b32 v[34:35], v11 offset0:33 offset1:41
	ds_read2_b32 v[36:37], v11 offset1:8
	ds_read2_b32 v[38:39], v11 offset0:66 offset1:74
	ds_read2_b32 v[40:41], v11 offset0:99 offset1:107
	ds_read2_b32 v[42:43], v11 offset0:132 offset1:140
	ds_read2_b32 v[44:45], v11 offset0:165 offset1:173
	ds_read2_b32 v[46:47], v11 offset0:198 offset1:206
	ds_read2_b32 v[48:49], v11 offset0:231 offset1:239
	s_waitcnt lgkmcnt(6)
	v_bfe_u32 v30, v36, 16, 1
	v_bfe_u32 v31, v34, 16, 1
	s_waitcnt lgkmcnt(5)
	s_waitcnt lgkmcnt(3)
	v_bfe_u32 v50, v42, 16, 1
	s_waitcnt lgkmcnt(2)
	v_bfe_u32 v51, v44, 16, 1
	v_add3_u32 v30, v36, v30, s46
	v_add3_u32 v31, v34, v31, s46
	v_add3_u32 v34, v42, v50, s46
	s_waitcnt lgkmcnt(1)
	v_bfe_u32 v52, v46, 16, 1
	v_add3_u32 v36, v44, v51, s46
	v_lshrrev_b32_e32 v30, 16, v30
	v_lshrrev_b32_e32 v34, 16, v34
	v_and_or_b32 v30, v31, s47, v30
	v_cvt_pk_bf16_f32 v31, v38, v40
	v_and_or_b32 v32, v36, s47, v34
	v_add3_u32 v33, v46, v52, s46
	s_waitcnt lgkmcnt(0)
	v_bfe_u32 v34, v48, 16, 1
	v_lshrrev_b32_e32 v33, 16, v33
	v_add3_u32 v34, v48, v34, s46
	v_and_or_b32 v33, v34, s47, v33
	v_or_b32_e32 v34, s0, v7
	v_mul_u32_u24_e32 v34, 0x1600, v34
	v_lshlrev_b32_e32 v50, 1, v34
	v_mov_b32_e32 v51, v3
	v_lshl_add_u64 v[50:51], v[4:5], 0, v[50:51]
	global_store_dwordx4 v[50:51], v[30:33], off
	v_bfe_u32 v34, v49, 16, 1
	v_add3_u32 v34, v49, v34, s46
	v_cvt_pk_bf16_f32 v30, v37, v35
	v_cvt_pk_bf16_f32 v31, v39, v41
	v_cvt_pk_bf16_f32 v32, v43, v45
	v_bfe_u32 v33, v47, 16, 1
	v_add3_u32 v33, v47, v33, s46
	v_lshrrev_b32_e32 v33, 16, v33
	v_and_or_b32 v33, v34, s47, v33
	v_or_b32_e32 v34, s0, v8
	v_mul_u32_u24_e32 v34, 0x1600, v34
	v_lshlrev_b32_e32 v34, 1, v34
	v_mov_b32_e32 v35, v3
	ds_read2_b32 v[36:37], v11 offset0:16 offset1:24
	v_lshl_add_u64 v[34:35], v[4:5], 0, v[34:35]
	global_store_dwordx4 v[34:35], v[30:33], off
	ds_read2_b32 v[34:35], v11 offset0:49 offset1:57
	ds_read2_b32 v[38:39], v11 offset0:82 offset1:90
	ds_read2_b32 v[40:41], v11 offset0:115 offset1:123
	s_waitcnt lgkmcnt(3)
	s_waitcnt lgkmcnt(2)
	ds_read2_b32 v[42:43], v11 offset0:148 offset1:156
	ds_read2_b32 v[44:45], v11 offset0:181 offset1:189
	v_cvt_pk_bf16_f32 v30, v36, v34
	s_waitcnt lgkmcnt(3)
	s_waitcnt lgkmcnt(2)
	ds_read2_b32 v[46:47], v11 offset0:214 offset1:222
	ds_read2_b32 v[48:49], v11 offset0:247 offset1:255
	v_cvt_pk_bf16_f32 v31, v38, v40
	s_waitcnt lgkmcnt(3)
	s_waitcnt lgkmcnt(2)
	v_cvt_pk_bf16_f32 v32, v42, v44
	s_waitcnt lgkmcnt(1)
	s_waitcnt lgkmcnt(0)
	v_cvt_pk_bf16_f32 v33, v46, v48
	v_or_b32_e32 v34, s0, v9
	v_mul_u32_u24_e32 v34, 0x1600, v34
	v_lshlrev_b32_e32 v50, 1, v34
	v_mov_b32_e32 v51, v3
	v_lshl_add_u64 v[50:51], v[4:5], 0, v[50:51]
	global_store_dwordx4 v[50:51], v[30:33], off
	v_bfe_u32 v34, v49, 16, 1
	v_add3_u32 v34, v49, v34, s46
	v_cvt_pk_bf16_f32 v30, v37, v35
	v_cvt_pk_bf16_f32 v31, v39, v41
	v_cvt_pk_bf16_f32 v32, v43, v45
	v_bfe_u32 v33, v47, 16, 1
	v_add3_u32 v33, v47, v33, s46
	v_lshrrev_b32_e32 v33, 16, v33
	v_and_or_b32 v33, v34, s47, v33
	v_or_b32_e32 v34, s0, v10
	v_mul_u32_u24_e32 v34, 0x1600, v34
	v_lshlrev_b32_e32 v34, 1, v34
	v_mov_b32_e32 v35, v3
	v_lshl_add_u64 v[4:5], v[4:5], 0, v[34:35]
	global_store_dwordx4 v[4:5], v[30:33], off
	s_waitcnt lgkmcnt(0)
	s_mov_b64 s[0:1], 0
.LBB0_51:
	s_andn2_b64 vcc, exec, s[0:1]
	s_cbranch_vccnz .LBB0_53
	s_add_i32 s0, s18, 0xc400
	s_and_b32 s1, s0, 0xffff
	s_mul_i32 s1, s1, 0xba2f
	s_lshr_b32 s1, s1, 24
	s_mul_i32 s63, s1, 0x160
	s_sub_i32 s63, s0, s63
	s_and_b32 s64, s63, 0xffff
	s_lshl_b32 s0, s64, 5
	s_lshl_b32 s64, s64, 4
	s_and_b32 s64, s64, 0x1f80
	s_and_b32 s65, s0, 0x60
	s_or_b32 s64, s64, s65
	s_bitcmp0_b32 s63, 2
	v_or_b32_e32 v4, s64, v6
	s_cselect_b32 s64, s24, s26
	s_cselect_b32 s63, s25, s27
	s_add_u32 s64, s64, s19
	v_lshl_or_b32 v30, s1, 6, v7
	s_addc_u32 s65, s63, 0
	v_lshlrev_b32_e32 v4, 2, v4
	v_mov_b32_e32 v5, v3
	v_mul_u32_u24_e32 v30, 0x1600, v30
	v_lshl_add_u64 v[4:5], s[64:65], 0, v[4:5]
	v_lshlrev_b32_e32 v30, 2, v30
	v_mov_b32_e32 v31, v3
	v_lshl_add_u64 v[4:5], v[4:5], 0, v[30:31]
	v_add_co_u32_e32 v34, vcc, s52, v4
	s_lshl_b32 s1, s1, 7
	s_nop 0
	v_addc_co_u32_e32 v35, vcc, 0, v5, vcc
	v_add_co_u32_e32 v38, vcc, s53, v4
	global_load_dwordx4 v[30:33], v[4:5], off
	s_nop 0
	global_load_dwordx4 v[34:37], v[34:35], off
	v_addc_co_u32_e32 v39, vcc, 0, v5, vcc
	v_add_co_u32_e32 v42, vcc, s54, v4
	s_add_u32 s64, s17, s1
	s_nop 0
	v_addc_co_u32_e32 v43, vcc, 0, v5, vcc
	v_add_co_u32_e32 v46, vcc, s55, v4
	global_load_dwordx4 v[38:41], v[38:39], off
	s_nop 0
	global_load_dwordx4 v[42:45], v[42:43], off
	v_addc_co_u32_e32 v47, vcc, 0, v5, vcc
	v_add_co_u32_e32 v50, vcc, s56, v4
	s_addc_u32 s65, s62, 0
	s_nop 0
	v_addc_co_u32_e32 v51, vcc, 0, v5, vcc
	global_load_dwordx4 v[46:49], v[46:47], off
	s_nop 0
	global_load_dwordx4 v[50:53], v[50:51], off
	v_add_co_u32_e32 v54, vcc, s57, v4
	s_nop 1
	v_addc_co_u32_e32 v55, vcc, 0, v5, vcc
	global_load_dwordx4 v[54:57], v[54:55], off
	v_add_co_u32_e32 v4, vcc, s58, v4
	s_nop 1
	v_addc_co_u32_e32 v5, vcc, 0, v5, vcc
	global_load_dwordx4 v[58:61], v[4:5], off
	v_lshl_add_u64 v[4:5], s[64:65], 0, v[2:3]
	v_lshl_add_u64 v[4:5], v[4:5], 0, s[6:7]
	s_waitcnt vmcnt(7)
	ds_write2_b32 v14, v30, v31 offset1:1
	ds_write2_b32 v14, v32, v33 offset0:2 offset1:3
	s_waitcnt vmcnt(6)
	ds_write2_b32 v15, v34, v35 offset1:1
	ds_write2_b32 v16, v36, v37 offset1:1
	s_waitcnt vmcnt(5)
	ds_write2_b32 v17, v38, v39 offset1:1
	ds_write2_b32 v18, v40, v41 offset1:1
	s_waitcnt vmcnt(4)
	ds_write2_b32 v19, v42, v43 offset1:1
	ds_write2_b32 v20, v44, v45 offset1:1
	s_waitcnt vmcnt(3)
	ds_write2_b32 v21, v46, v47 offset1:1
	ds_write2_b32 v22, v48, v49 offset1:1
	s_waitcnt vmcnt(2)
	ds_write2_b32 v23, v50, v51 offset1:1
	ds_write2_b32 v24, v52, v53 offset1:1
	s_waitcnt vmcnt(1)
	ds_write2_b32 v25, v54, v55 offset1:1
	ds_write2_b32 v26, v56, v57 offset1:1
	s_waitcnt vmcnt(0)
	ds_write2_b32 v27, v58, v59 offset1:1
	ds_write2_b32 v28, v60, v61 offset1:1
	s_waitcnt lgkmcnt(0)
	ds_read2_b32 v[34:35], v11 offset0:33 offset1:41
	ds_read2_b32 v[36:37], v11 offset1:8
	ds_read2_b32 v[38:39], v11 offset0:66 offset1:74
	ds_read2_b32 v[40:41], v11 offset0:99 offset1:107
	ds_read2_b32 v[42:43], v11 offset0:132 offset1:140
	ds_read2_b32 v[44:45], v11 offset0:165 offset1:173
	ds_read2_b32 v[46:47], v11 offset0:198 offset1:206
	s_waitcnt lgkmcnt(5)
	v_bfe_u32 v30, v36, 16, 1
	v_bfe_u32 v31, v34, 16, 1
	s_waitcnt lgkmcnt(2)
	v_bfe_u32 v48, v42, 16, 1
	s_waitcnt lgkmcnt(1)
	v_bfe_u32 v49, v44, 16, 1
	v_add3_u32 v30, v36, v30, s46
	v_add3_u32 v31, v34, v31, s46
	v_add3_u32 v34, v42, v48, s46
	v_add3_u32 v36, v44, v49, s46
	ds_read2_b32 v[48:49], v11 offset0:231 offset1:239
	v_lshrrev_b32_e32 v30, 16, v30
	v_lshrrev_b32_e32 v34, 16, v34
	v_and_or_b32 v30, v31, s47, v30
	v_cvt_pk_bf16_f32 v31, v38, v40
	s_waitcnt lgkmcnt(1)
	v_bfe_u32 v33, v46, 16, 1
	v_and_or_b32 v32, v36, s47, v34
	v_add3_u32 v33, v46, v33, s46
	s_waitcnt lgkmcnt(0)
	v_bfe_u32 v34, v48, 16, 1
	v_lshrrev_b32_e32 v33, 16, v33
	v_add3_u32 v34, v48, v34, s46
	v_and_or_b32 v33, v34, s47, v33
	v_or_b32_e32 v34, s0, v7
	v_lshlrev_b32_e32 v50, 12, v34
	v_mov_b32_e32 v51, v3
	v_lshl_add_u64 v[50:51], v[4:5], 0, v[50:51]
	global_store_dwordx4 v[50:51], v[30:33], off
	v_bfe_u32 v34, v49, 16, 1
	v_add3_u32 v34, v49, v34, s46
	v_cvt_pk_bf16_f32 v30, v37, v35
	v_cvt_pk_bf16_f32 v31, v39, v41
	v_cvt_pk_bf16_f32 v32, v43, v45
	v_bfe_u32 v33, v47, 16, 1
	v_add3_u32 v33, v47, v33, s46
	v_lshrrev_b32_e32 v33, 16, v33
	v_and_or_b32 v33, v34, s47, v33
	v_or_b32_e32 v34, s0, v8
	v_lshlrev_b32_e32 v34, 12, v34
	v_mov_b32_e32 v35, v3
	ds_read2_b32 v[36:37], v11 offset0:16 offset1:24
	v_lshl_add_u64 v[34:35], v[4:5], 0, v[34:35]
	global_store_dwordx4 v[34:35], v[30:33], off
	ds_read2_b32 v[34:35], v11 offset0:49 offset1:57
	ds_read2_b32 v[38:39], v11 offset0:82 offset1:90
	ds_read2_b32 v[40:41], v11 offset0:115 offset1:123
	s_waitcnt lgkmcnt(3)
	s_waitcnt lgkmcnt(2)
	ds_read2_b32 v[42:43], v11 offset0:148 offset1:156
	ds_read2_b32 v[44:45], v11 offset0:181 offset1:189
	v_cvt_pk_bf16_f32 v30, v36, v34
	s_waitcnt lgkmcnt(3)
	s_waitcnt lgkmcnt(2)
	ds_read2_b32 v[46:47], v11 offset0:214 offset1:222
	ds_read2_b32 v[48:49], v11 offset0:247 offset1:255
	v_cvt_pk_bf16_f32 v31, v38, v40
	s_waitcnt lgkmcnt(3)
	s_waitcnt lgkmcnt(2)
	v_cvt_pk_bf16_f32 v32, v42, v44
	s_waitcnt lgkmcnt(1)
	s_waitcnt lgkmcnt(0)
	v_cvt_pk_bf16_f32 v33, v46, v48
	v_or_b32_e32 v34, s0, v9
	v_lshlrev_b32_e32 v50, 12, v34
	v_mov_b32_e32 v51, v3
	v_lshl_add_u64 v[50:51], v[4:5], 0, v[50:51]
	global_store_dwordx4 v[50:51], v[30:33], off
	v_bfe_u32 v34, v49, 16, 1
	v_add3_u32 v34, v49, v34, s46
	v_cvt_pk_bf16_f32 v30, v37, v35
	v_cvt_pk_bf16_f32 v31, v39, v41
	v_cvt_pk_bf16_f32 v32, v43, v45
	v_bfe_u32 v33, v47, 16, 1
	v_add3_u32 v33, v47, v33, s46
	v_lshrrev_b32_e32 v33, 16, v33
	v_and_or_b32 v33, v34, s47, v33
	v_or_b32_e32 v34, s0, v10
	v_lshlrev_b32_e32 v34, 12, v34
	v_mov_b32_e32 v35, v3
	v_lshl_add_u64 v[4:5], v[4:5], 0, v[34:35]
	global_store_dwordx4 v[4:5], v[30:33], off
	s_waitcnt lgkmcnt(0)

.LBB0_54:
	s_andn2_b64 vcc, exec, s[0:1]
	s_cbranch_vccnz .LBB0_56
	s_lshl_b32 s0, s16, 24
	s_add_u32 s64, s30, s0
	s_addc_u32 s65, s31, 0
	s_lshl_b32 s0, s18, 5
	s_and_b32 s0, s0, 0x7e0
	s_add_i32 s1, s18, 0xcc00
	v_or_b32_e32 v4, s0, v6
	s_and_b32 s1, s1, 0xffc0
	v_or_b32_e32 v30, s1, v7
	v_lshlrev_b32_e32 v4, 2, v4
	v_mov_b32_e32 v5, v3
	v_lshl_add_u64 v[4:5], s[64:65], 0, v[4:5]
	v_lshlrev_b32_e32 v30, 13, v30
	v_mov_b32_e32 v31, v3
	v_lshl_add_u64 v[4:5], v[4:5], 0, v[30:31]
	v_add_co_u32_e32 v34, vcc, s38, v4
	s_lshl_b32 s1, s1, 1
	s_nop 0
	v_addc_co_u32_e32 v35, vcc, 0, v5, vcc
	v_add_co_u32_e32 v38, vcc, s39, v4
	global_load_dwordx4 v[30:33], v[4:5], off
	s_nop 0
	global_load_dwordx4 v[34:37], v[34:35], off
	v_addc_co_u32_e32 v39, vcc, 0, v5, vcc
	v_add_co_u32_e32 v42, vcc, s41, v4
	s_add_u32 s64, s17, s1
	s_nop 0
	v_addc_co_u32_e32 v43, vcc, 0, v5, vcc
	v_add_co_u32_e32 v46, vcc, s42, v4
	global_load_dwordx4 v[38:41], v[38:39], off
	s_nop 0
	global_load_dwordx4 v[42:45], v[42:43], off
	v_addc_co_u32_e32 v47, vcc, 0, v5, vcc
	v_add_co_u32_e32 v50, vcc, s43, v4
	s_addc_u32 s65, s62, 0
	s_nop 0
	v_addc_co_u32_e32 v51, vcc, 0, v5, vcc
	global_load_dwordx4 v[46:49], v[46:47], off
	s_nop 0
	global_load_dwordx4 v[50:53], v[50:51], off
	v_add_co_u32_e32 v54, vcc, s44, v4
	s_nop 1
	v_addc_co_u32_e32 v55, vcc, 0, v5, vcc
	global_load_dwordx4 v[54:57], v[54:55], off
	v_add_co_u32_e32 v4, vcc, s45, v4
	s_nop 1
	v_addc_co_u32_e32 v5, vcc, 0, v5, vcc
	global_load_dwordx4 v[58:61], v[4:5], off
	v_lshl_add_u64 v[4:5], s[64:65], 0, v[2:3]
	v_lshl_add_u64 v[4:5], v[4:5], 0, s[8:9]
	s_waitcnt vmcnt(7)
	ds_write2_b32 v14, v30, v31 offset1:1
	ds_write2_b32 v14, v32, v33 offset0:2 offset1:3
	s_waitcnt vmcnt(6)
	ds_write2_b32 v15, v34, v35 offset1:1
	ds_write2_b32 v16, v36, v37 offset1:1
	s_waitcnt vmcnt(5)
	ds_write2_b32 v17, v38, v39 offset1:1
	ds_write2_b32 v18, v40, v41 offset1:1
	s_waitcnt vmcnt(4)
	ds_write2_b32 v19, v42, v43 offset1:1
	ds_write2_b32 v20, v44, v45 offset1:1
	s_waitcnt vmcnt(3)
	ds_write2_b32 v21, v46, v47 offset1:1
	ds_write2_b32 v22, v48, v49 offset1:1
	s_waitcnt vmcnt(2)
	ds_write2_b32 v23, v50, v51 offset1:1
	ds_write2_b32 v24, v52, v53 offset1:1
	s_waitcnt vmcnt(1)
	ds_write2_b32 v25, v54, v55 offset1:1
	ds_write2_b32 v26, v56, v57 offset1:1
	s_waitcnt vmcnt(0)
	ds_write2_b32 v27, v58, v59 offset1:1
	ds_write2_b32 v28, v60, v61 offset1:1
	s_waitcnt lgkmcnt(0)
	ds_read2_b32 v[34:35], v11 offset0:33 offset1:41
	ds_read2_b32 v[36:37], v11 offset1:8
	ds_read2_b32 v[38:39], v11 offset0:66 offset1:74
	ds_read2_b32 v[40:41], v11 offset0:99 offset1:107
	ds_read2_b32 v[42:43], v11 offset0:132 offset1:140
	ds_read2_b32 v[44:45], v11 offset0:165 offset1:173
	ds_read2_b32 v[46:47], v11 offset0:198 offset1:206
	ds_read2_b32 v[48:49], v11 offset0:231 offset1:239
	s_waitcnt lgkmcnt(6)
	v_bfe_u32 v30, v36, 16, 1
	v_bfe_u32 v31, v34, 16, 1
	s_waitcnt lgkmcnt(5)
	s_waitcnt lgkmcnt(3)
	v_bfe_u32 v50, v42, 16, 1
	s_waitcnt lgkmcnt(2)
	v_bfe_u32 v51, v44, 16, 1
	v_add3_u32 v30, v36, v30, s46
	v_add3_u32 v31, v34, v31, s46
	v_add3_u32 v34, v42, v50, s46
	s_waitcnt lgkmcnt(1)
	v_bfe_u32 v52, v46, 16, 1
	v_add3_u32 v36, v44, v51, s46
	v_lshrrev_b32_e32 v30, 16, v30
	v_lshrrev_b32_e32 v34, 16, v34
	v_and_or_b32 v30, v31, s47, v30
	v_cvt_pk_bf16_f32 v31, v38, v40
	v_and_or_b32 v32, v36, s47, v34
	v_add3_u32 v33, v46, v52, s46
	s_waitcnt lgkmcnt(0)
	v_bfe_u32 v34, v48, 16, 1
	v_lshrrev_b32_e32 v33, 16, v33
	v_add3_u32 v34, v48, v34, s46
	v_and_or_b32 v33, v34, s47, v33
	v_or_b32_e32 v34, s0, v7
	v_lshlrev_b32_e32 v50, 12, v34
	v_mov_b32_e32 v51, v3
	v_lshl_add_u64 v[50:51], v[4:5], 0, v[50:51]
	global_store_dwordx4 v[50:51], v[30:33], off
	v_bfe_u32 v34, v49, 16, 1
	v_add3_u32 v34, v49, v34, s46
	v_cvt_pk_bf16_f32 v30, v37, v35
	v_cvt_pk_bf16_f32 v31, v39, v41
	v_cvt_pk_bf16_f32 v32, v43, v45
	v_bfe_u32 v33, v47, 16, 1
	v_add3_u32 v33, v47, v33, s46
	v_lshrrev_b32_e32 v33, 16, v33
	v_and_or_b32 v33, v34, s47, v33
	v_or_b32_e32 v34, s0, v8
	v_lshlrev_b32_e32 v34, 12, v34
	v_mov_b32_e32 v35, v3
	ds_read2_b32 v[36:37], v11 offset0:16 offset1:24
	v_lshl_add_u64 v[34:35], v[4:5], 0, v[34:35]
	global_store_dwordx4 v[34:35], v[30:33], off
	ds_read2_b32 v[34:35], v11 offset0:49 offset1:57
	ds_read2_b32 v[38:39], v11 offset0:82 offset1:90
	ds_read2_b32 v[40:41], v11 offset0:115 offset1:123
	s_waitcnt lgkmcnt(3)
	s_waitcnt lgkmcnt(2)
	ds_read2_b32 v[42:43], v11 offset0:148 offset1:156
	ds_read2_b32 v[44:45], v11 offset0:181 offset1:189
	v_cvt_pk_bf16_f32 v30, v36, v34
	s_waitcnt lgkmcnt(3)
	s_waitcnt lgkmcnt(2)
	ds_read2_b32 v[46:47], v11 offset0:214 offset1:222
	ds_read2_b32 v[48:49], v11 offset0:247 offset1:255
	v_cvt_pk_bf16_f32 v31, v38, v40
	s_waitcnt lgkmcnt(3)
	s_waitcnt lgkmcnt(2)
	v_cvt_pk_bf16_f32 v32, v42, v44
	s_waitcnt lgkmcnt(1)
	s_waitcnt lgkmcnt(0)
	v_cvt_pk_bf16_f32 v33, v46, v48
	v_or_b32_e32 v34, s0, v9
	v_lshlrev_b32_e32 v50, 12, v34
	v_mov_b32_e32 v51, v3
	v_lshl_add_u64 v[50:51], v[4:5], 0, v[50:51]
	global_store_dwordx4 v[50:51], v[30:33], off
	v_bfe_u32 v34, v49, 16, 1
	v_add3_u32 v34, v49, v34, s46
	v_cvt_pk_bf16_f32 v30, v37, v35
	v_cvt_pk_bf16_f32 v31, v39, v41
	v_cvt_pk_bf16_f32 v32, v43, v45
	v_bfe_u32 v33, v47, 16, 1
	v_add3_u32 v33, v47, v33, s46
	v_lshrrev_b32_e32 v33, 16, v33
	v_and_or_b32 v33, v34, s47, v33
	v_or_b32_e32 v34, s0, v10
	v_lshlrev_b32_e32 v34, 12, v34
	v_mov_b32_e32 v35, v3
	v_lshl_add_u64 v[4:5], v[4:5], 0, v[34:35]
	global_store_dwordx4 v[4:5], v[30:33], off
	s_waitcnt lgkmcnt(0)

.LBB0_57:
	s_andn2_b64 vcc, exec, s[0:1]
	s_cbranch_vccnz .LBB0_59
	s_lshl_b32 s0, s16, 24
	s_add_u32 s64, s22, s0
	s_addc_u32 s65, s23, 0
	s_lshl_b32 s0, s18, 5
	s_and_b32 s0, s0, 0x7e0
	s_add_i32 s1, s18, 0xd400
	v_or_b32_e32 v4, s0, v6
	s_and_b32 s1, s1, 0xffc0
	v_or_b32_e32 v30, s1, v7
	v_lshlrev_b32_e32 v4, 2, v4
	v_mov_b32_e32 v5, v3
	v_lshl_add_u64 v[4:5], s[64:65], 0, v[4:5]
	v_lshlrev_b32_e32 v30, 13, v30
	v_mov_b32_e32 v31, v3
	v_lshl_add_u64 v[4:5], v[4:5], 0, v[30:31]
	v_add_co_u32_e32 v34, vcc, s38, v4
	s_lshl_b32 s1, s1, 1
	s_nop 0
	v_addc_co_u32_e32 v35, vcc, 0, v5, vcc
	v_add_co_u32_e32 v38, vcc, s39, v4
	global_load_dwordx4 v[30:33], v[4:5], off
	s_nop 0
	global_load_dwordx4 v[34:37], v[34:35], off
	v_addc_co_u32_e32 v39, vcc, 0, v5, vcc
	v_add_co_u32_e32 v42, vcc, s41, v4
	s_add_u32 s64, s17, s1
	s_nop 0
	v_addc_co_u32_e32 v43, vcc, 0, v5, vcc
	v_add_co_u32_e32 v46, vcc, s42, v4
	global_load_dwordx4 v[38:41], v[38:39], off
	s_nop 0
	global_load_dwordx4 v[42:45], v[42:43], off
	v_addc_co_u32_e32 v47, vcc, 0, v5, vcc
	v_add_co_u32_e32 v50, vcc, s43, v4
	s_addc_u32 s65, s62, 0
	s_nop 0
	v_addc_co_u32_e32 v51, vcc, 0, v5, vcc
	global_load_dwordx4 v[46:49], v[46:47], off
	s_nop 0
	global_load_dwordx4 v[50:53], v[50:51], off
	v_add_co_u32_e32 v54, vcc, s44, v4
	s_nop 1
	v_addc_co_u32_e32 v55, vcc, 0, v5, vcc
	global_load_dwordx4 v[54:57], v[54:55], off
	v_add_co_u32_e32 v4, vcc, s45, v4
	s_nop 1
	v_addc_co_u32_e32 v5, vcc, 0, v5, vcc
	global_load_dwordx4 v[58:61], v[4:5], off
	v_lshl_add_u64 v[4:5], s[64:65], 0, v[2:3]
	v_lshl_add_u64 v[4:5], v[4:5], 0, s[12:13]
	s_waitcnt vmcnt(7)
	ds_write2_b32 v14, v30, v31 offset1:1
	ds_write2_b32 v14, v32, v33 offset0:2 offset1:3
	s_waitcnt vmcnt(6)
	ds_write2_b32 v15, v34, v35 offset1:1
	ds_write2_b32 v16, v36, v37 offset1:1
	s_waitcnt vmcnt(5)
	ds_write2_b32 v17, v38, v39 offset1:1
	ds_write2_b32 v18, v40, v41 offset1:1
	s_waitcnt vmcnt(4)
	ds_write2_b32 v19, v42, v43 offset1:1
	ds_write2_b32 v20, v44, v45 offset1:1
	s_waitcnt vmcnt(3)
	ds_write2_b32 v21, v46, v47 offset1:1
	ds_write2_b32 v22, v48, v49 offset1:1
	s_waitcnt vmcnt(2)
	ds_write2_b32 v23, v50, v51 offset1:1
	ds_write2_b32 v24, v52, v53 offset1:1
	s_waitcnt vmcnt(1)
	ds_write2_b32 v25, v54, v55 offset1:1
	ds_write2_b32 v26, v56, v57 offset1:1
	s_waitcnt vmcnt(0)
	ds_write2_b32 v27, v58, v59 offset1:1
	ds_write2_b32 v28, v60, v61 offset1:1
	s_waitcnt lgkmcnt(0)
	ds_read2_b32 v[34:35], v11 offset0:33 offset1:41
	ds_read2_b32 v[36:37], v11 offset1:8
	ds_read2_b32 v[38:39], v11 offset0:66 offset1:74
	ds_read2_b32 v[40:41], v11 offset0:99 offset1:107
	ds_read2_b32 v[42:43], v11 offset0:132 offset1:140
	ds_read2_b32 v[44:45], v11 offset0:165 offset1:173
	ds_read2_b32 v[46:47], v11 offset0:198 offset1:206
	ds_read2_b32 v[48:49], v11 offset0:231 offset1:239
	s_waitcnt lgkmcnt(6)
	v_bfe_u32 v30, v36, 16, 1
	v_bfe_u32 v31, v34, 16, 1
	s_waitcnt lgkmcnt(5)
	s_waitcnt lgkmcnt(3)
	v_bfe_u32 v50, v42, 16, 1
	s_waitcnt lgkmcnt(2)
	v_bfe_u32 v51, v44, 16, 1
	v_add3_u32 v30, v36, v30, s46
	v_add3_u32 v31, v34, v31, s46
	v_add3_u32 v34, v42, v50, s46
	s_waitcnt lgkmcnt(1)
	v_bfe_u32 v52, v46, 16, 1
	v_add3_u32 v36, v44, v51, s46
	v_lshrrev_b32_e32 v30, 16, v30
	v_lshrrev_b32_e32 v34, 16, v34
	v_and_or_b32 v30, v31, s47, v30
	v_cvt_pk_bf16_f32 v31, v38, v40
	v_and_or_b32 v32, v36, s47, v34
	v_add3_u32 v33, v46, v52, s46
	s_waitcnt lgkmcnt(0)
	v_bfe_u32 v34, v48, 16, 1
	v_lshrrev_b32_e32 v33, 16, v33
	v_add3_u32 v34, v48, v34, s46
	v_and_or_b32 v33, v34, s47, v33
	v_or_b32_e32 v34, s0, v7
	v_lshlrev_b32_e32 v50, 12, v34
	v_mov_b32_e32 v51, v3
	v_lshl_add_u64 v[50:51], v[4:5], 0, v[50:51]
	global_store_dwordx4 v[50:51], v[30:33], off
	v_bfe_u32 v34, v49, 16, 1
	v_add3_u32 v34, v49, v34, s46
	v_cvt_pk_bf16_f32 v30, v37, v35
	v_cvt_pk_bf16_f32 v31, v39, v41
	v_cvt_pk_bf16_f32 v32, v43, v45
	v_bfe_u32 v33, v47, 16, 1
	v_add3_u32 v33, v47, v33, s46
	v_lshrrev_b32_e32 v33, 16, v33
	v_and_or_b32 v33, v34, s47, v33
	v_or_b32_e32 v34, s0, v8
	v_lshlrev_b32_e32 v34, 12, v34
	v_mov_b32_e32 v35, v3
	ds_read2_b32 v[36:37], v11 offset0:16 offset1:24
	v_lshl_add_u64 v[34:35], v[4:5], 0, v[34:35]
	global_store_dwordx4 v[34:35], v[30:33], off
	ds_read2_b32 v[34:35], v11 offset0:49 offset1:57
	ds_read2_b32 v[38:39], v11 offset0:82 offset1:90
	ds_read2_b32 v[40:41], v11 offset0:115 offset1:123
	s_waitcnt lgkmcnt(3)
	s_waitcnt lgkmcnt(2)
	ds_read2_b32 v[42:43], v11 offset0:148 offset1:156
	ds_read2_b32 v[44:45], v11 offset0:181 offset1:189
	v_cvt_pk_bf16_f32 v30, v36, v34
	s_waitcnt lgkmcnt(3)
	s_waitcnt lgkmcnt(2)
	ds_read2_b32 v[46:47], v11 offset0:214 offset1:222
	ds_read2_b32 v[48:49], v11 offset0:247 offset1:255
	v_cvt_pk_bf16_f32 v31, v38, v40
	s_waitcnt lgkmcnt(3)
	s_waitcnt lgkmcnt(2)
	v_cvt_pk_bf16_f32 v32, v42, v44
	s_waitcnt lgkmcnt(1)
	s_waitcnt lgkmcnt(0)
	v_cvt_pk_bf16_f32 v33, v46, v48
	v_or_b32_e32 v34, s0, v9
	v_lshlrev_b32_e32 v50, 12, v34
	v_mov_b32_e32 v51, v3
	v_lshl_add_u64 v[50:51], v[4:5], 0, v[50:51]
	global_store_dwordx4 v[50:51], v[30:33], off
	v_bfe_u32 v34, v49, 16, 1
	v_add3_u32 v34, v49, v34, s46
	v_cvt_pk_bf16_f32 v30, v37, v35
	v_cvt_pk_bf16_f32 v31, v39, v41
	v_cvt_pk_bf16_f32 v32, v43, v45
	v_bfe_u32 v33, v47, 16, 1
	v_add3_u32 v33, v47, v33, s46
	v_lshrrev_b32_e32 v33, 16, v33
	v_and_or_b32 v33, v34, s47, v33
	v_or_b32_e32 v34, s0, v10
	v_lshlrev_b32_e32 v34, 12, v34
	v_mov_b32_e32 v35, v3
	v_lshl_add_u64 v[4:5], v[4:5], 0, v[34:35]
	global_store_dwordx4 v[4:5], v[30:33], off
	s_waitcnt lgkmcnt(0)

.LBB0_60:
	s_andn2_b64 vcc, exec, s[0:1]
	s_cbranch_vccnz .LBB0_62
	s_lshl_b32 s0, s16, 23
	s_add_u32 s64, s20, s0
	s_addc_u32 s65, s21, 0
	s_lshl_b32 s0, s18, 5
	s_and_b32 s0, s0, 0x7e0
	s_add_i32 s1, s18, 0xd800
	v_or_b32_e32 v4, s0, v6
	s_and_b32 s1, s1, 0xffc0
	v_or_b32_e32 v30, s1, v7
	v_lshlrev_b32_e32 v4, 2, v4
	v_mov_b32_e32 v5, v3
	v_lshl_add_u64 v[4:5], s[64:65], 0, v[4:5]
	v_lshlrev_b32_e32 v30, 13, v30
	v_mov_b32_e32 v31, v3
	v_lshl_add_u64 v[4:5], v[4:5], 0, v[30:31]
	v_add_co_u32_e32 v34, vcc, s38, v4
	s_lshl_b32 s1, s1, 1
	s_nop 0
	v_addc_co_u32_e32 v35, vcc, 0, v5, vcc
	v_add_co_u32_e32 v38, vcc, s39, v4
	global_load_dwordx4 v[30:33], v[4:5], off
	s_nop 0
	global_load_dwordx4 v[34:37], v[34:35], off
	v_addc_co_u32_e32 v39, vcc, 0, v5, vcc
	v_add_co_u32_e32 v42, vcc, s41, v4
	s_add_u32 s64, s17, s1
	s_nop 0
	v_addc_co_u32_e32 v43, vcc, 0, v5, vcc
	v_add_co_u32_e32 v46, vcc, s42, v4
	global_load_dwordx4 v[38:41], v[38:39], off
	s_nop 0
	global_load_dwordx4 v[42:45], v[42:43], off
	v_addc_co_u32_e32 v47, vcc, 0, v5, vcc
	v_add_co_u32_e32 v50, vcc, s43, v4
	s_addc_u32 s65, s62, 0
	s_nop 0
	v_addc_co_u32_e32 v51, vcc, 0, v5, vcc
	global_load_dwordx4 v[46:49], v[46:47], off
	s_nop 0
	global_load_dwordx4 v[50:53], v[50:51], off
	v_add_co_u32_e32 v54, vcc, s44, v4
	s_nop 1
	v_addc_co_u32_e32 v55, vcc, 0, v5, vcc
	global_load_dwordx4 v[54:57], v[54:55], off
	v_add_co_u32_e32 v4, vcc, s45, v4
	s_nop 1
	v_addc_co_u32_e32 v5, vcc, 0, v5, vcc
	global_load_dwordx4 v[58:61], v[4:5], off
	v_lshl_add_u64 v[4:5], s[64:65], 0, v[2:3]
	v_lshl_add_u64 v[4:5], v[4:5], 0, s[14:15]
	s_waitcnt vmcnt(7)
	ds_write2_b32 v14, v30, v31 offset1:1
	ds_write2_b32 v14, v32, v33 offset0:2 offset1:3
	s_waitcnt vmcnt(6)
	ds_write2_b32 v15, v34, v35 offset1:1
	ds_write2_b32 v16, v36, v37 offset1:1
	s_waitcnt vmcnt(5)
	ds_write2_b32 v17, v38, v39 offset1:1
	ds_write2_b32 v18, v40, v41 offset1:1
	s_waitcnt vmcnt(4)
	ds_write2_b32 v19, v42, v43 offset1:1
	ds_write2_b32 v20, v44, v45 offset1:1
	s_waitcnt vmcnt(3)
	ds_write2_b32 v21, v46, v47 offset1:1
	ds_write2_b32 v22, v48, v49 offset1:1
	s_waitcnt vmcnt(2)
	ds_write2_b32 v23, v50, v51 offset1:1
	ds_write2_b32 v24, v52, v53 offset1:1
	s_waitcnt vmcnt(1)
	ds_write2_b32 v25, v54, v55 offset1:1
	ds_write2_b32 v26, v56, v57 offset1:1
	s_waitcnt vmcnt(0)
	ds_write2_b32 v27, v58, v59 offset1:1
	ds_write2_b32 v28, v60, v61 offset1:1
	s_waitcnt lgkmcnt(0)
	ds_read2_b32 v[34:35], v11 offset0:33 offset1:41
	ds_read2_b32 v[36:37], v11 offset1:8
	ds_read2_b32 v[38:39], v11 offset0:66 offset1:74
	ds_read2_b32 v[40:41], v11 offset0:99 offset1:107
	ds_read2_b32 v[42:43], v11 offset0:132 offset1:140
	ds_read2_b32 v[44:45], v11 offset0:165 offset1:173
	ds_read2_b32 v[46:47], v11 offset0:198 offset1:206
	ds_read2_b32 v[48:49], v11 offset0:231 offset1:239
	s_waitcnt lgkmcnt(6)
	v_bfe_u32 v30, v36, 16, 1
	v_bfe_u32 v31, v34, 16, 1
	s_waitcnt lgkmcnt(5)
	s_waitcnt lgkmcnt(3)
	v_bfe_u32 v50, v42, 16, 1
	s_waitcnt lgkmcnt(2)
	v_bfe_u32 v51, v44, 16, 1
	v_add3_u32 v30, v36, v30, s46
	v_add3_u32 v31, v34, v31, s46
	v_add3_u32 v34, v42, v50, s46
	s_waitcnt lgkmcnt(1)
	v_bfe_u32 v52, v46, 16, 1
	v_add3_u32 v36, v44, v51, s46
	v_lshrrev_b32_e32 v30, 16, v30
	v_lshrrev_b32_e32 v34, 16, v34
	v_and_or_b32 v30, v31, s47, v30
	v_cvt_pk_bf16_f32 v31, v38, v40
	v_and_or_b32 v32, v36, s47, v34
	v_add3_u32 v33, v46, v52, s46
	s_waitcnt lgkmcnt(0)
	v_bfe_u32 v34, v48, 16, 1
	v_lshrrev_b32_e32 v33, 16, v33
	v_add3_u32 v34, v48, v34, s46
	v_and_or_b32 v33, v34, s47, v33
	v_or_b32_e32 v34, s0, v7
	v_lshlrev_b32_e32 v50, 12, v34
	v_mov_b32_e32 v51, v3
	v_lshl_add_u64 v[50:51], v[4:5], 0, v[50:51]
	global_store_dwordx4 v[50:51], v[30:33], off
	v_bfe_u32 v34, v49, 16, 1
	v_add3_u32 v34, v49, v34, s46
	v_cvt_pk_bf16_f32 v30, v37, v35
	v_cvt_pk_bf16_f32 v31, v39, v41
	v_cvt_pk_bf16_f32 v32, v43, v45
	v_bfe_u32 v33, v47, 16, 1
	v_add3_u32 v33, v47, v33, s46
	v_lshrrev_b32_e32 v33, 16, v33
	v_and_or_b32 v33, v34, s47, v33
	v_or_b32_e32 v34, s0, v8
	v_lshlrev_b32_e32 v34, 12, v34
	v_mov_b32_e32 v35, v3
	ds_read2_b32 v[36:37], v11 offset0:16 offset1:24
	v_lshl_add_u64 v[34:35], v[4:5], 0, v[34:35]
	global_store_dwordx4 v[34:35], v[30:33], off
	ds_read2_b32 v[34:35], v11 offset0:49 offset1:57
	ds_read2_b32 v[38:39], v11 offset0:82 offset1:90
	ds_read2_b32 v[40:41], v11 offset0:115 offset1:123
	s_waitcnt lgkmcnt(3)
	s_waitcnt lgkmcnt(2)
	ds_read2_b32 v[42:43], v11 offset0:148 offset1:156
	ds_read2_b32 v[44:45], v11 offset0:181 offset1:189
	v_cvt_pk_bf16_f32 v30, v36, v34
	s_waitcnt lgkmcnt(3)
	s_waitcnt lgkmcnt(2)
	ds_read2_b32 v[46:47], v11 offset0:214 offset1:222
	ds_read2_b32 v[48:49], v11 offset0:247 offset1:255
	v_cvt_pk_bf16_f32 v31, v38, v40
	s_waitcnt lgkmcnt(3)
	s_waitcnt lgkmcnt(2)
	v_cvt_pk_bf16_f32 v32, v42, v44
	s_waitcnt lgkmcnt(1)
	s_waitcnt lgkmcnt(0)
	v_cvt_pk_bf16_f32 v33, v46, v48
	v_or_b32_e32 v34, s0, v9
	v_lshlrev_b32_e32 v50, 12, v34
	v_mov_b32_e32 v51, v3
	v_lshl_add_u64 v[50:51], v[4:5], 0, v[50:51]
	global_store_dwordx4 v[50:51], v[30:33], off
	v_bfe_u32 v34, v49, 16, 1
	v_add3_u32 v34, v49, v34, s46
	v_cvt_pk_bf16_f32 v30, v37, v35
	v_cvt_pk_bf16_f32 v31, v39, v41
	v_cvt_pk_bf16_f32 v32, v43, v45
	v_bfe_u32 v33, v47, 16, 1
	v_add3_u32 v33, v47, v33, s46
	v_lshrrev_b32_e32 v33, 16, v33
	v_and_or_b32 v33, v34, s47, v33
	v_or_b32_e32 v34, s0, v10
	v_lshlrev_b32_e32 v34, 12, v34
	v_mov_b32_e32 v35, v3
	v_lshl_add_u64 v[4:5], v[4:5], 0, v[34:35]
	global_store_dwordx4 v[4:5], v[30:33], off
	s_waitcnt lgkmcnt(0)

.LBB0_208:
	s_waitcnt vmcnt(0)
	v_mul_f32_e32 v150, v33, v33
	v_mul_f32_e32 v151, v35, v35
	v_fmac_f32_e32 v150, v32, v32
	v_fmac_f32_e32 v151, v34, v34
	v_add_f32_e32 v150, v150, v151
	v_mul_f32_e32 v151, v29, v29
	v_mul_f32_e32 v152, v31, v31
	v_fmac_f32_e32 v151, v28, v28
	v_fmac_f32_e32 v152, v30, v30
	v_add_f32_e32 v151, v151, v152
	v_add_f32_e32 v150, v151, v150
	s_waitcnt vmcnt(4)
	v_mul_f32_e32 v151, v25, v25
	v_mul_f32_e32 v152, v27, v27
	v_fmac_f32_e32 v151, v24, v24
	v_fmac_f32_e32 v152, v26, v26
	v_add_f32_e32 v151, v151, v152
	v_add_f32_e32 v150, v151, v150
	v_mul_f32_e32 v151, v21, v21
	v_mul_f32_e32 v152, v23, v23
	v_fmac_f32_e32 v151, v20, v20
	v_fmac_f32_e32 v152, v22, v22
	v_add_f32_e32 v151, v151, v152
	v_add_f32_e32 v150, v151, v150
	s_waitcnt vmcnt(3)
	v_mul_f32_e32 v151, v17, v17
	v_mul_f32_e32 v152, v19, v19
	v_fmac_f32_e32 v151, v16, v16
	v_fmac_f32_e32 v152, v18, v18
	v_add_f32_e32 v151, v151, v152
	v_add_f32_e32 v150, v151, v150
	s_waitcnt vmcnt(2)
	v_mul_f32_e32 v151, v13, v13
	v_mul_f32_e32 v152, v15, v15
	v_fmac_f32_e32 v151, v12, v12
	v_fmac_f32_e32 v152, v14, v14
	v_add_f32_e32 v151, v151, v152
	v_add_f32_e32 v150, v151, v150
	s_waitcnt vmcnt(1)
	v_mul_f32_e32 v151, v9, v9
	v_mul_f32_e32 v152, v11, v11
	v_fmac_f32_e32 v151, v8, v8
	v_fmac_f32_e32 v152, v10, v10
	v_add_f32_e32 v151, v151, v152
	v_add_f32_e32 v150, v151, v150
	s_waitcnt vmcnt(0)
	v_mul_f32_e32 v151, v5, v5
	v_mul_f32_e32 v152, v7, v7
	v_fmac_f32_e32 v151, v4, v4
	v_fmac_f32_e32 v152, v6, v6
	v_add_f32_e32 v151, v151, v152
	v_add_f32_e32 v150, v151, v150
	ds_swizzle_b32 v151, v150 offset:swizzle(SWAP,1)
	s_ashr_i32 s27, s26, 31
	s_add_i32 s6, s6, 1
	s_waitcnt lgkmcnt(0)
	v_add_f32_e32 v150, v150, v151
	ds_swizzle_b32 v151, v150 offset:swizzle(SWAP,2)
	s_waitcnt lgkmcnt(0)
	v_add_f32_e32 v150, v150, v151
	ds_swizzle_b32 v151, v150 offset:swizzle(SWAP,4)
	s_waitcnt lgkmcnt(0)
	v_add_f32_e32 v150, v150, v151
	ds_swizzle_b32 v151, v150 offset:swizzle(SWAP,8)
	s_waitcnt lgkmcnt(0)
	v_add_f32_e32 v150, v150, v151
	ds_swizzle_b32 v151, v150 offset:swizzle(SWAP,16)
	s_waitcnt lgkmcnt(0)
	v_add_f32_e32 v150, v150, v151
	s_nop 0
	v_readlane_b32 s9, v150, 32
	v_readlane_b32 s8, v150, 0
	s_nop 0
	v_mov_b32_e32 v150, s9
	v_add_f32_e32 v150, s8, v150
	v_fmamk_f32 v150, v150, 0x3a000000, v1
	v_mul_f32_e32 v151, 0x4f800000, v150
	v_cmp_gt_f32_e32 vcc, s74, v150
	s_nop 1
	v_cndmask_b32_e32 v150, v150, v151, vcc
	v_sqrt_f32_e32 v151, v150
	s_nop 0
	v_add_u32_e32 v152, -1, v151
	v_fma_f32 v153, -v152, v151, v150
	v_cmp_ge_f32_e64 s[38:39], 0, v153
	v_add_u32_e32 v153, 1, v151
	s_nop 0
	v_cndmask_b32_e64 v152, v151, v152, s[38:39]
	v_fma_f32 v151, -v153, v151, v150
	v_cmp_lt_f32_e64 s[38:39], 0, v151
	s_nop 1
	v_cndmask_b32_e64 v151, v152, v153, s[38:39]
	v_mul_f32_e32 v152, 0x37800000, v151
	v_cndmask_b32_e32 v151, v151, v152, vcc
	v_cmp_class_f32_e32 vcc, v150, v240
	s_nop 1
	v_cndmask_b32_e32 v150, v151, v150, vcc
	v_div_scale_f32 v151, s[16:17], v150, v150, 1.0
	v_rcp_f32_e32 v152, v151
	s_lshl_b64 s[16:17], s[26:27], 12
	s_cmp_lg_u32 s6, 12
	v_fma_f32 v153, -v151, v152, 1.0
	v_fmac_f32_e32 v152, v153, v152
	v_div_scale_f32 v153, vcc, 1.0, v150, 1.0
	v_mul_f32_e32 v154, v153, v152
	v_fma_f32 v155, -v151, v154, v153
	v_fmac_f32_e32 v154, v155, v152
	v_fma_f32 v151, -v151, v154, v153
	v_div_fmas_f32 v151, v151, v152, v154
	v_div_fixup_f32 v150, v151, v150, 1.0
	v_pk_mul_f32 v[32:33], v[32:33], v[150:151] op_sel_hi:[1,0]
	v_pk_mul_f32 v[28:29], v[28:29], v[150:151] op_sel_hi:[1,0]
	v_pk_fma_f32 v[32:33], v[48:49], v[32:33], v[44:45]
	v_pk_mul_f32 v[30:31], v[30:31], v[150:151] op_sel_hi:[1,0]
	v_pk_mul_f32 v[34:35], v[34:35], v[150:151] op_sel_hi:[1,0]
	v_pk_fma_f32 v[152:153], v[66:67], v[30:31], v[42:43]
	v_pk_fma_f32 v[30:31], v[64:65], v[28:29], v[40:41]
	v_pk_fma_f32 v[34:35], v[50:51], v[34:35], v[46:47]
	v_cvt_pk_bf16_f32 v28, v32, v33
	v_cvt_pk_bf16_f32 v29, v34, v35
	v_bfe_u32 v32, v30, 16, 1
	v_add3_u32 v30, v30, v32, s75
	v_bfe_u32 v32, v31, 16, 1
	v_lshrrev_b32_e32 v30, 16, v30
	v_add3_u32 v31, v31, v32, s75
	v_and_or_b32 v30, v31, s1, v30
	v_pk_mul_f32 v[24:25], v[24:25], v[150:151] op_sel_hi:[1,0]
	v_cvt_pk_bf16_f32 v31, v152, v153
	v_lshl_add_u64 v[32:33], v[142:143], 0, s[16:17]
	v_pk_fma_f32 v[24:25], v[92:93], v[24:25], v[76:77]
	v_pk_mul_f32 v[20:21], v[20:21], v[150:151] op_sel_hi:[1,0]
	v_pk_mul_f32 v[22:23], v[22:23], v[150:151] op_sel_hi:[1,0]
	global_store_dwordx4 v[32:33], v[28:31], off
	v_pk_mul_f32 v[26:27], v[26:27], v[150:151] op_sel_hi:[1,0]
	v_pk_mul_f32 v[16:17], v[16:17], v[150:151] op_sel_hi:[1,0]
	v_pk_fma_f32 v[28:29], v[98:99], v[22:23], v[74:75]
	v_pk_fma_f32 v[22:23], v[96:97], v[20:21], v[72:73]
	v_pk_fma_f32 v[26:27], v[94:95], v[26:27], v[78:79]
	v_cvt_pk_bf16_f32 v20, v24, v25
	v_cvt_pk_bf16_f32 v21, v26, v27
	v_bfe_u32 v24, v22, 16, 1
	v_add3_u32 v22, v22, v24, s75
	v_bfe_u32 v24, v23, 16, 1
	v_lshrrev_b32_e32 v22, 16, v22
	v_add3_u32 v23, v23, v24, s75
	v_and_or_b32 v22, v23, s1, v22
	v_cvt_pk_bf16_f32 v23, v28, v29
	v_pk_fma_f32 v[16:17], v[108:109], v[16:17], v[104:105]
	v_pk_mul_f32 v[12:13], v[12:13], v[150:151] op_sel_hi:[1,0]
	v_pk_mul_f32 v[14:15], v[14:15], v[150:151] op_sel_hi:[1,0]
	global_store_dwordx4 v[32:33], v[20:23], off offset:1024
	v_pk_mul_f32 v[18:19], v[18:19], v[150:151] op_sel_hi:[1,0]
	v_pk_mul_f32 v[8:9], v[8:9], v[150:151] op_sel_hi:[1,0]
	v_pk_fma_f32 v[20:21], v[114:115], v[14:15], v[102:103]
	v_pk_fma_f32 v[14:15], v[112:113], v[12:13], v[100:101]
	v_pk_fma_f32 v[18:19], v[110:111], v[18:19], v[106:107]
	v_cvt_pk_bf16_f32 v12, v16, v17
	v_cvt_pk_bf16_f32 v13, v18, v19
	v_bfe_u32 v16, v14, 16, 1
	v_add3_u32 v14, v14, v16, s75
	v_bfe_u32 v16, v15, 16, 1
	v_lshrrev_b32_e32 v14, 16, v14
	v_add3_u32 v15, v15, v16, s75
	v_and_or_b32 v14, v15, s1, v14
	v_cvt_pk_bf16_f32 v15, v20, v21
	v_pk_fma_f32 v[8:9], v[124:125], v[8:9], v[120:121]
	v_pk_mul_f32 v[4:5], v[4:5], v[150:151] op_sel_hi:[1,0]
	v_pk_mul_f32 v[6:7], v[6:7], v[150:151] op_sel_hi:[1,0]
	global_store_dwordx4 v[32:33], v[12:15], off offset:2048
	v_pk_mul_f32 v[10:11], v[10:11], v[150:151] op_sel_hi:[1,0]
	v_mov_b32_e32 v16, v68
	v_pk_fma_f32 v[12:13], v[130:131], v[6:7], v[118:119]
	v_pk_fma_f32 v[6:7], v[128:129], v[4:5], v[116:117]
	v_pk_fma_f32 v[10:11], v[126:127], v[10:11], v[122:123]
	v_cvt_pk_bf16_f32 v4, v8, v9
	v_cvt_pk_bf16_f32 v5, v10, v11
	v_bfe_u32 v8, v6, 16, 1
	v_add3_u32 v6, v6, v8, s75
	v_bfe_u32 v8, v7, 16, 1
	v_lshrrev_b32_e32 v6, 16, v6
	v_add3_u32 v7, v7, v8, s75
	v_and_or_b32 v6, v7, s1, v6
	v_cvt_pk_bf16_f32 v7, v12, v13
	global_store_dwordx4 v[32:33], v[4:7], off offset:3072
	v_mov_b32_e32 v8, v84
	v_mov_b32_e32 v9, v85
	v_mov_b32_e32 v4, v88
	v_mov_b32_e32 v5, v89
	v_mov_b32_e32 v6, v90
	v_mov_b32_e32 v7, v91
	v_mov_b32_e32 v10, v86
	v_mov_b32_e32 v11, v87
	v_mov_b32_e32 v12, v80
	v_mov_b32_e32 v13, v81
	v_mov_b32_e32 v14, v82
	v_mov_b32_e32 v15, v83
	v_mov_b32_e32 v17, v69
	v_mov_b32_e32 v18, v70
	v_mov_b32_e32 v19, v71
	v_mov_b32_e32 v20, v60
	v_mov_b32_e32 v21, v61
	v_mov_b32_e32 v22, v62
	v_mov_b32_e32 v23, v63
	v_mov_b32_e32 v24, v56
	v_mov_b32_e32 v25, v57
	v_mov_b32_e32 v26, v58
	v_mov_b32_e32 v27, v59
	v_mov_b32_e32 v28, v52
	v_mov_b32_e32 v29, v53
	v_mov_b32_e32 v30, v54
	v_mov_b32_e32 v31, v55
	v_mov_b32_e32 v32, v36
	v_mov_b32_e32 v33, v37
	v_mov_b32_e32 v34, v38
	v_mov_b32_e32 v35, v39
	s_cbranch_scc0 .LBB0_216

.LBB0_946:
	v_mul_f32_e32 v2, v139, v139
	v_mul_f32_e32 v146, v141, v141
	v_fmac_f32_e32 v2, v138, v138
	v_fmac_f32_e32 v146, v140, v140
	v_add_f32_e32 v2, v2, v146
	v_mul_f32_e32 v146, v135, v135
	v_mul_f32_e32 v147, v137, v137
	v_fmac_f32_e32 v146, v134, v134
	v_fmac_f32_e32 v147, v136, v136
	v_add_f32_e32 v146, v146, v147
	v_add_f32_e32 v2, v146, v2
	v_mul_f32_e32 v146, v131, v131
	v_mul_f32_e32 v147, v133, v133
	v_fmac_f32_e32 v146, v130, v130
	v_fmac_f32_e32 v147, v132, v132
	v_add_f32_e32 v146, v146, v147
	v_add_f32_e32 v2, v146, v2
	v_mul_f32_e32 v146, v127, v127
	v_mul_f32_e32 v147, v129, v129
	v_fmac_f32_e32 v146, v126, v126
	v_fmac_f32_e32 v147, v128, v128
	v_add_f32_e32 v146, v146, v147
	v_add_f32_e32 v2, v146, v2
	v_mul_f32_e32 v146, v123, v123
	v_mul_f32_e32 v147, v125, v125
	v_fmac_f32_e32 v146, v122, v122
	v_fmac_f32_e32 v147, v124, v124
	v_add_f32_e32 v146, v146, v147
	v_add_f32_e32 v2, v146, v2
	v_mul_f32_e32 v146, v119, v119
	v_mul_f32_e32 v147, v121, v121
	v_fmac_f32_e32 v146, v118, v118
	v_fmac_f32_e32 v147, v120, v120
	v_add_f32_e32 v146, v146, v147
	v_add_f32_e32 v2, v146, v2
	v_mul_f32_e32 v146, v115, v115
	v_mul_f32_e32 v147, v117, v117
	v_fmac_f32_e32 v146, v114, v114
	v_fmac_f32_e32 v147, v116, v116
	v_add_f32_e32 v146, v146, v147
	v_add_f32_e32 v2, v146, v2
	v_mul_f32_e32 v146, v111, v111
	v_mul_f32_e32 v147, v113, v113
	v_fmac_f32_e32 v146, v110, v110
	v_fmac_f32_e32 v147, v112, v112
	v_add_f32_e32 v146, v146, v147
	v_add_f32_e32 v2, v146, v2
	ds_swizzle_b32 v146, v2 offset:swizzle(SWAP,1)
	s_ashr_i32 s21, s20, 31
	s_add_i32 s6, s6, 1
	s_waitcnt lgkmcnt(0)
	v_add_f32_e32 v2, v2, v146
	ds_swizzle_b32 v146, v2 offset:swizzle(SWAP,2)
	s_waitcnt lgkmcnt(0)
	v_add_f32_e32 v2, v2, v146
	ds_swizzle_b32 v146, v2 offset:swizzle(SWAP,4)
	s_waitcnt lgkmcnt(0)
	v_add_f32_e32 v2, v2, v146
	ds_swizzle_b32 v146, v2 offset:swizzle(SWAP,8)
	s_waitcnt lgkmcnt(0)
	v_add_f32_e32 v2, v2, v146
	ds_swizzle_b32 v146, v2 offset:swizzle(SWAP,16)
	s_waitcnt lgkmcnt(0)
	v_add_f32_e32 v2, v2, v146
	s_nop 0
	v_readlane_b32 s9, v2, 32
	v_readlane_b32 s8, v2, 0
	s_nop 0
	v_mov_b32_e32 v2, s9
	v_add_f32_e32 v2, s8, v2
	v_fmamk_f32 v2, v2, 0x3a000000, v1
	v_mul_f32_e32 v146, 0x4f800000, v2
	v_cmp_gt_f32_e32 vcc, s74, v2
	s_nop 1
	v_cndmask_b32_e32 v2, v2, v146, vcc
	v_sqrt_f32_e32 v146, v2
	s_nop 0
	v_add_u32_e32 v147, -1, v146
	v_fma_f32 v148, -v147, v146, v2
	v_cmp_ge_f32_e64 s[38:39], 0, v148
	v_add_u32_e32 v148, 1, v146
	s_nop 0
	v_cndmask_b32_e64 v147, v146, v147, s[38:39]
	v_fma_f32 v146, -v148, v146, v2
	v_cmp_lt_f32_e64 s[38:39], 0, v146
	s_nop 1
	v_cndmask_b32_e64 v146, v147, v148, s[38:39]
	v_mul_f32_e32 v147, 0x37800000, v146
	v_cndmask_b32_e32 v146, v146, v147, vcc
	v_cmp_class_f32_e32 vcc, v2, v240
	s_nop 1
	v_cndmask_b32_e32 v2, v146, v2, vcc
	v_div_scale_f32 v146, s[8:9], v2, v2, 1.0
	v_rcp_f32_e32 v147, v146
	s_lshl_b64 s[8:9], s[20:21], 12
	s_cmp_lg_u32 s6, 12
	v_fma_f32 v148, -v146, v147, 1.0
	v_fmac_f32_e32 v147, v148, v147
	v_div_scale_f32 v148, vcc, 1.0, v2, 1.0
	v_mul_f32_e32 v149, v148, v147
	v_fma_f32 v150, -v146, v149, v148
	v_fmac_f32_e32 v149, v150, v147
	v_fma_f32 v146, -v146, v149, v148
	v_div_fmas_f32 v146, v146, v147, v149
	v_div_fixup_f32 v2, v146, v2, 1.0
	v_pk_mul_f32 v[138:139], v[138:139], v[2:3] op_sel_hi:[1,0]
	v_pk_mul_f32 v[134:135], v[134:135], v[2:3] op_sel_hi:[1,0]
	v_pk_fma_f32 v[138:139], v[44:45], v[138:139], v[40:41]
	v_pk_mul_f32 v[136:137], v[136:137], v[2:3] op_sel_hi:[1,0]
	v_pk_mul_f32 v[140:141], v[140:141], v[2:3] op_sel_hi:[1,0]
	v_pk_fma_f32 v[146:147], v[50:51], v[136:137], v[38:39]
	v_pk_fma_f32 v[136:137], v[48:49], v[134:135], v[36:37]
	v_pk_fma_f32 v[140:141], v[46:47], v[140:141], v[42:43]
	v_cvt_pk_bf16_f32 v134, v138, v139
	v_cvt_pk_bf16_f32 v135, v140, v141
	v_bfe_u32 v138, v136, 16, 1
	v_add3_u32 v136, v136, v138, s75
	v_bfe_u32 v138, v137, 16, 1
	v_lshrrev_b32_e32 v136, 16, v136
	v_add3_u32 v137, v137, v138, s75
	v_and_or_b32 v136, v137, s1, v136
	v_pk_mul_f32 v[130:131], v[130:131], v[2:3] op_sel_hi:[1,0]
	v_cvt_pk_bf16_f32 v137, v146, v147
	v_lshl_add_u64 v[138:139], v[100:101], 0, s[8:9]
	v_pk_fma_f32 v[130:131], v[60:61], v[130:131], v[56:57]
	v_pk_mul_f32 v[126:127], v[126:127], v[2:3] op_sel_hi:[1,0]
	v_pk_mul_f32 v[128:129], v[128:129], v[2:3] op_sel_hi:[1,0]
	global_store_dwordx4 v[138:139], v[134:137], off
	v_pk_mul_f32 v[132:133], v[132:133], v[2:3] op_sel_hi:[1,0]
	v_pk_mul_f32 v[122:123], v[122:123], v[2:3] op_sel_hi:[1,0]
	v_pk_fma_f32 v[134:135], v[66:67], v[128:129], v[54:55]
	v_pk_fma_f32 v[128:129], v[64:65], v[126:127], v[52:53]
	v_pk_fma_f32 v[132:133], v[62:63], v[132:133], v[58:59]
	v_cvt_pk_bf16_f32 v126, v130, v131
	v_cvt_pk_bf16_f32 v127, v132, v133
	v_bfe_u32 v130, v128, 16, 1
	v_add3_u32 v128, v128, v130, s75
	v_bfe_u32 v130, v129, 16, 1
	v_lshrrev_b32_e32 v128, 16, v128
	v_add3_u32 v129, v129, v130, s75
	v_and_or_b32 v128, v129, s1, v128
	v_cvt_pk_bf16_f32 v129, v134, v135
	v_pk_fma_f32 v[122:123], v[76:77], v[122:123], v[72:73]
	v_pk_mul_f32 v[118:119], v[118:119], v[2:3] op_sel_hi:[1,0]
	v_pk_mul_f32 v[120:121], v[120:121], v[2:3] op_sel_hi:[1,0]
	global_store_dwordx4 v[138:139], v[126:129], off offset:1024
	v_pk_mul_f32 v[124:125], v[124:125], v[2:3] op_sel_hi:[1,0]
	v_pk_mul_f32 v[114:115], v[114:115], v[2:3] op_sel_hi:[1,0]
	v_pk_fma_f32 v[126:127], v[82:83], v[120:121], v[70:71]
	v_pk_fma_f32 v[120:121], v[80:81], v[118:119], v[68:69]
	v_pk_fma_f32 v[124:125], v[78:79], v[124:125], v[74:75]
	v_cvt_pk_bf16_f32 v118, v122, v123
	v_cvt_pk_bf16_f32 v119, v124, v125
	v_bfe_u32 v122, v120, 16, 1
	v_add3_u32 v120, v120, v122, s75
	v_bfe_u32 v122, v121, 16, 1
	v_lshrrev_b32_e32 v120, 16, v120
	v_add3_u32 v121, v121, v122, s75
	v_and_or_b32 v120, v121, s1, v120
	v_pk_fma_f32 v[114:115], v[92:93], v[114:115], v[88:89]
	v_cvt_pk_bf16_f32 v121, v126, v127
	v_pk_mul_f32 v[116:117], v[116:117], v[2:3] op_sel_hi:[1,0]
	v_pk_mul_f32 v[110:111], v[110:111], v[2:3] op_sel_hi:[1,0]
	v_pk_mul_f32 v[112:113], v[112:113], v[2:3] op_sel_hi:[1,0]
	v_bfe_u32 v2, v114, 16, 1
	global_store_dwordx4 v[138:139], v[118:121], off offset:2048
	v_add3_u32 v2, v114, v2, s75
	v_pk_fma_f32 v[116:117], v[94:95], v[116:117], v[90:91]
	v_pk_fma_f32 v[118:119], v[98:99], v[112:113], v[86:87]
	v_pk_fma_f32 v[112:113], v[96:97], v[110:111], v[84:85]
	v_bfe_u32 v110, v115, 16, 1
	v_lshrrev_b32_e32 v2, 16, v2
	v_add3_u32 v110, v115, v110, s75
	v_and_or_b32 v110, v110, s1, v2
	v_cvt_pk_bf16_f32 v111, v116, v117
	v_bfe_u32 v2, v112, 16, 1
	v_add3_u32 v2, v112, v2, s75
	v_bfe_u32 v112, v113, 16, 1
	v_lshrrev_b32_e32 v2, 16, v2
	v_add3_u32 v112, v113, v112, s75
	v_and_or_b32 v112, v112, s1, v2
	v_cvt_pk_bf16_f32 v113, v118, v119
	global_store_dwordx4 v[138:139], v[110:113], off offset:3072
	v_mov_b32_e32 v114, v28
	v_mov_b32_e32 v115, v29
	v_mov_b32_e32 v110, v32
	v_mov_b32_e32 v111, v33
	v_mov_b32_e32 v112, v34
	v_mov_b32_e32 v113, v35
	v_mov_b32_e32 v116, v30
	v_mov_b32_e32 v117, v31
	v_mov_b32_e32 v118, v24
	v_mov_b32_e32 v119, v25
	v_mov_b32_e32 v120, v26
	v_mov_b32_e32 v121, v27
	v_mov_b32_e32 v122, v20
	v_mov_b32_e32 v123, v21
	v_mov_b32_e32 v124, v22
	v_mov_b32_e32 v125, v23
	v_mov_b32_e32 v126, v16
	v_mov_b32_e32 v127, v17
	v_mov_b32_e32 v128, v18
	v_mov_b32_e32 v129, v19
	v_mov_b32_e32 v130, v12
	v_mov_b32_e32 v131, v13
	v_mov_b32_e32 v132, v14
	v_mov_b32_e32 v133, v15
	v_mov_b32_e32 v134, v8
	v_mov_b32_e32 v135, v9
	v_mov_b32_e32 v136, v10
	v_mov_b32_e32 v137, v11
	v_mov_b32_e32 v138, v4
	v_mov_b32_e32 v139, v5
	v_mov_b32_e32 v140, v6
	v_mov_b32_e32 v141, v7
	s_cbranch_scc0 .LBB0_951

.LBB0_1047:
	s_lshl_b32 s18, s21, 6
	v_or_b32_e32 v2, s18, v20
	v_ashrrev_i32_e32 v17, 31, v16
	v_lshl_add_u64 v[16:17], v[16:17], 2, s[14:15]
	v_or_b32_e32 v29, 8, v2
	v_mad_i64_i32 v[30:31], s[8:9], v2, s0, v[16:17]
	v_mad_i64_i32 v[34:35], s[8:9], v29, s0, v[16:17]
	global_load_dwordx4 v[30:33], v[30:31], off
	v_or_b32_e32 v29, 16, v2
	global_load_dwordx4 v[34:37], v[34:35], off
	v_mad_i64_i32 v[38:39], s[8:9], v29, s0, v[16:17]
	global_load_dwordx4 v[38:41], v[38:39], off
	v_or_b32_e32 v29, 24, v2
	v_mad_i64_i32 v[42:43], s[8:9], v29, s0, v[16:17]
	global_load_dwordx4 v[42:45], v[42:43], off
	v_or_b32_e32 v29, 32, v2
	v_mad_i64_i32 v[46:47], s[8:9], v29, s0, v[16:17]
	global_load_dwordx4 v[46:49], v[46:47], off
	v_or_b32_e32 v29, 40, v2
	v_mad_i64_i32 v[50:51], s[8:9], v29, s0, v[16:17]
	global_load_dwordx4 v[50:53], v[50:51], off
	v_or_b32_e32 v29, 48, v2
	v_mad_i64_i32 v[54:55], s[8:9], v29, s0, v[16:17]
	global_load_dwordx4 v[54:57], v[54:55], off
	v_or_b32_e32 v2, 56, v2
	v_mad_i64_i32 v[16:17], s[8:9], v2, s0, v[16:17]
	global_load_dwordx4 v[58:61], v[16:17], off
	v_add_u32_e32 v2, v21, v22
	v_add_u32_e32 v16, 0x420, v2
	s_ashr_i32 s19, s18, 31
	s_waitcnt vmcnt(0)
	ds_write2_b32 v2, v30, v31 offset1:1
	ds_write2_b32 v2, v32, v33 offset0:2 offset1:3
	ds_write2_b32 v16, v34, v35 offset1:1
	v_add_u32_e32 v16, 0x428, v2
	ds_write2_b32 v16, v36, v37 offset1:1
	v_add_u32_e32 v16, 0x840, v2
	ds_write2_b32 v16, v38, v39 offset1:1
	v_add_u32_e32 v16, 0x848, v2
	ds_write2_b32 v16, v40, v41 offset1:1
	v_add_u32_e32 v16, 0xc60, v2
	ds_write2_b32 v16, v42, v43 offset1:1
	v_add_u32_e32 v16, 0xc68, v2
	ds_write2_b32 v16, v44, v45 offset1:1
	v_add_u32_e32 v16, 0x1080, v2
	ds_write2_b32 v16, v46, v47 offset1:1
	v_add_u32_e32 v16, 0x1088, v2
	ds_write2_b32 v16, v48, v49 offset1:1
	v_add_u32_e32 v16, 0x14a0, v2
	ds_write2_b32 v16, v50, v51 offset1:1
	v_add_u32_e32 v16, 0x14a8, v2
	ds_write2_b32 v16, v52, v53 offset1:1
	v_add_u32_e32 v16, 0x18c0, v2
	ds_write2_b32 v16, v54, v55 offset1:1
	v_add_u32_e32 v16, 0x18c8, v2
	ds_write2_b32 v16, v56, v57 offset1:1
	v_add_u32_e32 v16, 0x1ce0, v2
	v_add_u32_e32 v2, 0x1ce8, v2
	ds_write2_b32 v16, v58, v59 offset1:1
	ds_write2_b32 v2, v60, v61 offset1:1
	s_waitcnt lgkmcnt(0)
	ds_read2_b32 v[34:35], v26 offset0:33 offset1:41
	ds_read2_b32 v[36:37], v26 offset1:8
	ds_read2_b32 v[38:39], v26 offset0:66 offset1:74
	ds_read2_b32 v[40:41], v26 offset0:99 offset1:107
	ds_read2_b32 v[42:43], v26 offset0:132 offset1:140
	ds_read2_b32 v[44:45], v26 offset0:165 offset1:173
	ds_read2_b32 v[46:47], v26 offset0:198 offset1:206
	ds_read2_b32 v[48:49], v26 offset0:231 offset1:239
	s_waitcnt lgkmcnt(0)
	v_cvt_pk_bf16_f32 v30, v36, v34
	v_cvt_pk_bf16_f32 v31, v38, v40
	v_cvt_pk_bf16_f32 v32, v42, v44
	v_add_u32_e32 v50, s20, v20
	v_cvt_pk_bf16_f32 v33, v46, v48
	v_ashrrev_i32_e32 v51, 31, v50
	v_bfe_u32 v2, v37, 16, 1
	v_lshl_add_u64 v[16:17], s[18:19], 1, v[4:5]
	v_lshlrev_b64 v[52:53], 12, v[50:51]
	v_add3_u32 v2, v37, v2, s75
	v_bfe_u32 v29, v35, 16, 1
	v_lshl_add_u64 v[52:53], v[16:17], 0, v[52:53]
	v_lshrrev_b32_e32 v2, 16, v2
	v_add3_u32 v29, v35, v29, s75
	global_store_dwordx4 v[52:53], v[30:33], off
	v_add_u32_e32 v34, 8, v50
	v_ashrrev_i32_e32 v35, 31, v34
	v_and_or_b32 v30, v29, s1, v2
	v_cvt_pk_bf16_f32 v31, v39, v41
	v_cvt_pk_bf16_f32 v32, v43, v45
	v_lshlrev_b64 v[34:35], 12, v[34:35]
	v_cvt_pk_bf16_f32 v33, v47, v49
	v_lshl_add_u64 v[34:35], v[16:17], 0, v[34:35]
	global_store_dwordx4 v[34:35], v[30:33], off
	ds_read2_b32 v[34:35], v26 offset0:49 offset1:57
	ds_read2_b32 v[36:37], v26 offset0:16 offset1:24
	ds_read2_b32 v[38:39], v26 offset0:82 offset1:90
	ds_read2_b32 v[40:41], v26 offset0:115 offset1:123
	ds_read2_b32 v[42:43], v26 offset0:148 offset1:156
	ds_read2_b32 v[44:45], v26 offset0:181 offset1:189
	ds_read2_b32 v[46:47], v26 offset0:214 offset1:222
	ds_read2_b32 v[48:49], v26 offset0:247 offset1:255
	s_waitcnt lgkmcnt(7)
	s_waitcnt lgkmcnt(6)
	v_cvt_pk_bf16_f32 v30, v36, v34
	s_waitcnt lgkmcnt(5)
	s_waitcnt lgkmcnt(4)
	v_cvt_pk_bf16_f32 v31, v38, v40
	s_waitcnt lgkmcnt(3)
	s_waitcnt lgkmcnt(2)
	v_cvt_pk_bf16_f32 v32, v42, v44
	s_waitcnt lgkmcnt(1)
	s_waitcnt lgkmcnt(0)
	v_add_u32_e32 v52, 16, v50
	v_cvt_pk_bf16_f32 v33, v46, v48
	v_ashrrev_i32_e32 v53, 31, v52
	v_bfe_u32 v2, v37, 16, 1
	v_lshlrev_b64 v[52:53], 12, v[52:53]
	v_add3_u32 v2, v37, v2, s75
	v_bfe_u32 v29, v35, 16, 1
	v_lshl_add_u64 v[52:53], v[16:17], 0, v[52:53]
	v_lshrrev_b32_e32 v2, 16, v2
	v_add3_u32 v29, v35, v29, s75
	global_store_dwordx4 v[52:53], v[30:33], off
	v_add_u32_e32 v34, 24, v50
	v_ashrrev_i32_e32 v35, 31, v34
	v_and_or_b32 v30, v29, s1, v2
	v_cvt_pk_bf16_f32 v31, v39, v41
	v_cvt_pk_bf16_f32 v32, v43, v45
	v_lshlrev_b64 v[34:35], 12, v[34:35]
	v_cvt_pk_bf16_f32 v33, v47, v49
	v_lshl_add_u64 v[16:17], v[16:17], 0, v[34:35]
	global_store_dwordx4 v[16:17], v[30:33], off
	s_waitcnt lgkmcnt(0)

.LBB0_1049:
	s_cmpk_gt_i32 s7, 0x27ff
	s_mov_b64 s[16:17], -1
	s_cbranch_scc0 .LBB0_1067
	s_cmpk_gt_u32 s7, 0x2bff
	s_cbranch_scc0 .LBB0_1064
	s_cmpk_gt_u32 s7, 0x33ff
	s_cbranch_scc0 .LBB0_1061
	s_cmpk_gt_u32 s7, 0x3bff
	s_cbranch_scc0 .LBB0_1058
	s_cmpk_gt_u32 s7, 0x67ff
	s_cbranch_scc0 .LBB0_1055
	s_and_b32 s16, s6, 0x7e0
	s_add_i32 s8, s7, 0x9800
	v_or_b32_e32 v2, s16, v19
	s_and_b32 s8, s8, 0xffc0
	v_or_b32_e32 v29, s8, v20
	v_lshlrev_b32_e32 v2, 2, v2
	v_lshl_add_u64 v[16:17], s[38:39], 0, v[2:3]
	v_lshlrev_b32_e32 v2, 13, v29
	v_lshl_add_u64 v[16:17], v[16:17], 0, v[2:3]
	v_add_co_u32_e32 v34, vcc, 0x10000, v16
	global_load_dwordx4 v[30:33], v[16:17], off
	s_nop 0
	v_addc_co_u32_e32 v35, vcc, 0, v17, vcc
	global_load_dwordx4 v[34:37], v[34:35], off
	v_add_co_u32_e32 v38, vcc, 0x20000, v16
	v_add_u32_e32 v2, v21, v22
	s_nop 0
	v_addc_co_u32_e32 v39, vcc, 0, v17, vcc
	global_load_dwordx4 v[38:41], v[38:39], off
	v_add_co_u32_e32 v42, vcc, 0x30000, v16
	s_lshl_b32 s36, s8, 1
	s_nop 0
	v_addc_co_u32_e32 v43, vcc, 0, v17, vcc
	global_load_dwordx4 v[42:45], v[42:43], off
	v_add_co_u32_e32 v46, vcc, 0x40000, v16
	s_nop 1
	v_addc_co_u32_e32 v47, vcc, 0, v17, vcc
	global_load_dwordx4 v[46:49], v[46:47], off
	v_add_co_u32_e32 v50, vcc, 0x50000, v16
	s_nop 1
	v_addc_co_u32_e32 v51, vcc, 0, v17, vcc
	global_load_dwordx4 v[50:53], v[50:51], off
	v_add_co_u32_e32 v54, vcc, 0x60000, v16
	s_nop 1
	v_addc_co_u32_e32 v55, vcc, 0, v17, vcc
	global_load_dwordx4 v[54:57], v[54:55], off
	v_add_co_u32_e32 v16, vcc, 0x70000, v16
	s_nop 1
	v_addc_co_u32_e32 v17, vcc, 0, v17, vcc
	global_load_dwordx4 v[58:61], v[16:17], off
	v_add_u32_e32 v16, 0x420, v2
	s_waitcnt vmcnt(0)
	ds_write2_b32 v2, v30, v31 offset1:1
	ds_write2_b32 v2, v32, v33 offset0:2 offset1:3
	ds_write2_b32 v16, v34, v35 offset1:1
	v_add_u32_e32 v16, 0x428, v2
	ds_write2_b32 v16, v36, v37 offset1:1
	v_add_u32_e32 v16, 0x840, v2
	ds_write2_b32 v16, v38, v39 offset1:1
	v_add_u32_e32 v16, 0x848, v2
	ds_write2_b32 v16, v40, v41 offset1:1
	v_add_u32_e32 v16, 0xc60, v2
	ds_write2_b32 v16, v42, v43 offset1:1
	v_add_u32_e32 v16, 0xc68, v2
	ds_write2_b32 v16, v44, v45 offset1:1
	v_add_u32_e32 v16, 0x1080, v2
	ds_write2_b32 v16, v46, v47 offset1:1
	v_add_u32_e32 v16, 0x1088, v2
	ds_write2_b32 v16, v48, v49 offset1:1
	v_add_u32_e32 v16, 0x14a0, v2
	ds_write2_b32 v16, v50, v51 offset1:1
	v_add_u32_e32 v16, 0x14a8, v2
	ds_write2_b32 v16, v52, v53 offset1:1
	v_add_u32_e32 v16, 0x18c0, v2
	ds_write2_b32 v16, v54, v55 offset1:1
	v_add_u32_e32 v16, 0x18c8, v2
	ds_write2_b32 v16, v56, v57 offset1:1
	v_add_u32_e32 v16, 0x1ce0, v2
	v_add_u32_e32 v2, 0x1ce8, v2
	ds_write2_b32 v16, v58, v59 offset1:1
	ds_write2_b32 v2, v60, v61 offset1:1
	s_waitcnt lgkmcnt(0)
	ds_read2_b32 v[34:35], v26 offset0:33 offset1:41
	ds_read2_b32 v[36:37], v26 offset1:8
	ds_read2_b32 v[38:39], v26 offset0:66 offset1:74
	ds_read2_b32 v[40:41], v26 offset0:99 offset1:107
	ds_read2_b32 v[42:43], v26 offset0:132 offset1:140
	ds_read2_b32 v[44:45], v26 offset0:165 offset1:173
	ds_read2_b32 v[46:47], v26 offset0:198 offset1:206
	ds_read2_b32 v[48:49], v26 offset0:231 offset1:239
	s_waitcnt lgkmcnt(0)
	v_cvt_pk_bf16_f32 v30, v36, v34
	v_cvt_pk_bf16_f32 v31, v38, v40
	v_cvt_pk_bf16_f32 v32, v42, v44
	v_cvt_pk_bf16_f32 v33, v46, v48
	v_or_b32_e32 v2, s16, v20
	v_mul_u32_u24_e32 v2, 0x1600, v2
	v_lshl_add_u64 v[16:17], v[6:7], 0, s[36:37]
	v_lshlrev_b32_e32 v2, 1, v2
	v_lshl_add_u64 v[50:51], v[16:17], 0, v[2:3]
	global_store_dwordx4 v[50:51], v[30:33], off
	s_nop 1
	v_cvt_pk_bf16_f32 v30, v37, v35
	v_cvt_pk_bf16_f32 v31, v39, v41
	v_cvt_pk_bf16_f32 v32, v43, v45
	v_cvt_pk_bf16_f32 v33, v47, v49
	v_or_b32_e32 v2, s16, v23
	v_mul_u32_u24_e32 v2, 0x1600, v2
	v_lshlrev_b32_e32 v2, 1, v2
	v_lshl_add_u64 v[34:35], v[16:17], 0, v[2:3]
	global_store_dwordx4 v[34:35], v[30:33], off
	ds_read2_b32 v[34:35], v26 offset0:16 offset1:24
	ds_read2_b32 v[36:37], v26 offset0:49 offset1:57
	ds_read2_b32 v[38:39], v26 offset0:82 offset1:90
	ds_read2_b32 v[40:41], v26 offset0:115 offset1:123
	ds_read2_b32 v[42:43], v26 offset0:148 offset1:156
	ds_read2_b32 v[44:45], v26 offset0:181 offset1:189
	ds_read2_b32 v[46:47], v26 offset0:214 offset1:222
	ds_read2_b32 v[48:49], v26 offset0:247 offset1:255
	s_waitcnt lgkmcnt(7)
	s_waitcnt lgkmcnt(6)
	v_cvt_pk_bf16_f32 v30, v34, v36
	s_waitcnt lgkmcnt(5)
	s_waitcnt lgkmcnt(4)
	v_cvt_pk_bf16_f32 v31, v38, v40
	s_waitcnt lgkmcnt(3)
	s_waitcnt lgkmcnt(2)
	v_cvt_pk_bf16_f32 v32, v42, v44
	s_waitcnt lgkmcnt(1)
	s_waitcnt lgkmcnt(0)
	v_cvt_pk_bf16_f32 v33, v46, v48
	v_or_b32_e32 v2, s16, v24
	v_mul_u32_u24_e32 v2, 0x1600, v2
	v_lshlrev_b32_e32 v2, 1, v2
	v_lshl_add_u64 v[50:51], v[16:17], 0, v[2:3]
	global_store_dwordx4 v[50:51], v[30:33], off
	s_nop 1
	v_cvt_pk_bf16_f32 v30, v35, v37
	v_cvt_pk_bf16_f32 v31, v39, v41
	v_cvt_pk_bf16_f32 v32, v43, v45
	v_cvt_pk_bf16_f32 v33, v47, v49
	v_or_b32_e32 v2, s16, v25
	v_mul_u32_u24_e32 v2, 0x1600, v2
	v_lshlrev_b32_e32 v2, 1, v2
	v_lshl_add_u64 v[16:17], v[16:17], 0, v[2:3]
	global_store_dwordx4 v[16:17], v[30:33], off
	s_waitcnt lgkmcnt(0)
	s_mov_b64 s[16:17], 0
.LBB0_1055:
	s_andn2_b64 vcc, exec, s[16:17]
	s_cbranch_vccnz .LBB0_1057
	s_add_i32 s8, s7, 0xc400
	s_and_b32 s9, s8, 0xffff
	s_mul_i32 s9, s9, 0xba2f
	s_lshr_b32 s17, s9, 24
	s_mul_i32 s9, s17, 0x160
	s_sub_i32 s8, s8, s9
	s_and_b32 s9, s8, 0xffff
	s_lshl_b32 s16, s9, 5
	s_lshl_b32 s9, s9, 4
	s_and_b32 s9, s9, 0x1f80
	s_and_b32 s18, s16, 0x60
	s_or_b32 s9, s9, s18
	s_bitcmp0_b32 s8, 2
	s_cselect_b32 s8, s44, s46
	v_or_b32_e32 v2, s9, v19
	s_cselect_b32 s9, s45, s47
	s_add_u32 s8, s8, s5
	s_addc_u32 s9, s9, s4
	v_lshl_or_b32 v29, s17, 6, v20
	v_lshlrev_b32_e32 v2, 2, v2
	v_lshl_add_u64 v[16:17], s[8:9], 0, v[2:3]
	v_mul_u32_u24_e32 v2, 0x1600, v29
	v_lshlrev_b32_e32 v2, 2, v2
	v_lshl_add_u64 v[16:17], v[16:17], 0, v[2:3]
	s_mov_b32 s8, 0x2c000
	v_add_co_u32_e32 v34, vcc, s8, v16
	s_mov_b32 s8, 0x58000
	s_nop 0
	v_addc_co_u32_e32 v35, vcc, 0, v17, vcc
	global_load_dwordx4 v[30:33], v[16:17], off
	v_add_co_u32_e32 v38, vcc, s8, v16
	global_load_dwordx4 v[34:37], v[34:35], off
	s_nop 0
	v_addc_co_u32_e32 v39, vcc, 0, v17, vcc
	s_mov_b32 s8, 0x84000
	global_load_dwordx4 v[38:41], v[38:39], off
	v_add_co_u32_e32 v42, vcc, s8, v16
	s_mov_b32 s8, 0xb0000
	s_nop 0
	v_addc_co_u32_e32 v43, vcc, 0, v17, vcc
	global_load_dwordx4 v[42:45], v[42:43], off
	v_add_co_u32_e32 v46, vcc, s8, v16
	s_mov_b32 s8, 0xdc000
	s_nop 0
	v_addc_co_u32_e32 v47, vcc, 0, v17, vcc
	global_load_dwordx4 v[46:49], v[46:47], off
	v_add_co_u32_e32 v50, vcc, s8, v16
	s_mov_b32 s8, 0x108000
	s_nop 0
	v_addc_co_u32_e32 v51, vcc, 0, v17, vcc
	global_load_dwordx4 v[50:53], v[50:51], off
	v_add_co_u32_e32 v54, vcc, s8, v16
	s_mov_b32 s8, 0x134000
	s_nop 0
	v_addc_co_u32_e32 v55, vcc, 0, v17, vcc
	global_load_dwordx4 v[54:57], v[54:55], off
	v_add_co_u32_e32 v16, vcc, s8, v16
	v_add_u32_e32 v2, v21, v22
	s_nop 0
	v_addc_co_u32_e32 v17, vcc, 0, v17, vcc
	global_load_dwordx4 v[58:61], v[16:17], off
	v_add_u32_e32 v16, 0x420, v2
	s_lshl_b32 s36, s17, 7
	s_waitcnt vmcnt(0)
	ds_write2_b32 v2, v30, v31 offset1:1
	ds_write2_b32 v2, v32, v33 offset0:2 offset1:3
	ds_write2_b32 v16, v34, v35 offset1:1
	v_add_u32_e32 v16, 0x428, v2
	ds_write2_b32 v16, v36, v37 offset1:1
	v_add_u32_e32 v16, 0x840, v2
	ds_write2_b32 v16, v38, v39 offset1:1
	v_add_u32_e32 v16, 0x848, v2
	ds_write2_b32 v16, v40, v41 offset1:1
	v_add_u32_e32 v16, 0xc60, v2
	ds_write2_b32 v16, v42, v43 offset1:1
	v_add_u32_e32 v16, 0xc68, v2
	ds_write2_b32 v16, v44, v45 offset1:1
	v_add_u32_e32 v16, 0x1080, v2
	ds_write2_b32 v16, v46, v47 offset1:1
	v_add_u32_e32 v16, 0x1088, v2
	ds_write2_b32 v16, v48, v49 offset1:1
	v_add_u32_e32 v16, 0x14a0, v2
	ds_write2_b32 v16, v50, v51 offset1:1
	v_add_u32_e32 v16, 0x14a8, v2
	ds_write2_b32 v16, v52, v53 offset1:1
	v_add_u32_e32 v16, 0x18c0, v2
	ds_write2_b32 v16, v54, v55 offset1:1
	v_add_u32_e32 v16, 0x18c8, v2
	ds_write2_b32 v16, v56, v57 offset1:1
	v_add_u32_e32 v16, 0x1ce0, v2
	v_add_u32_e32 v2, 0x1ce8, v2
	ds_write2_b32 v16, v58, v59 offset1:1
	ds_write2_b32 v2, v60, v61 offset1:1
	s_waitcnt lgkmcnt(0)
	ds_read2_b32 v[34:35], v26 offset0:33 offset1:41
	ds_read2_b32 v[36:37], v26 offset1:8
	ds_read2_b32 v[38:39], v26 offset0:66 offset1:74
	ds_read2_b32 v[40:41], v26 offset0:99 offset1:107
	ds_read2_b32 v[42:43], v26 offset0:132 offset1:140
	ds_read2_b32 v[44:45], v26 offset0:165 offset1:173
	ds_read2_b32 v[46:47], v26 offset0:198 offset1:206
	ds_read2_b32 v[48:49], v26 offset0:231 offset1:239
	s_waitcnt lgkmcnt(0)
	v_cvt_pk_bf16_f32 v30, v36, v34
	v_cvt_pk_bf16_f32 v31, v38, v40
	v_cvt_pk_bf16_f32 v32, v42, v44
	v_cvt_pk_bf16_f32 v33, v46, v48
	v_or_b32_e32 v2, s16, v20
	v_lshl_add_u64 v[16:17], v[8:9], 0, s[36:37]
	v_lshlrev_b32_e32 v2, 12, v2
	v_lshl_add_u64 v[50:51], v[16:17], 0, v[2:3]
	global_store_dwordx4 v[50:51], v[30:33], off
	s_nop 1
	v_cvt_pk_bf16_f32 v30, v37, v35
	v_cvt_pk_bf16_f32 v31, v39, v41
	v_cvt_pk_bf16_f32 v32, v43, v45
	v_cvt_pk_bf16_f32 v33, v47, v49
	v_or_b32_e32 v2, s16, v23
	v_lshlrev_b32_e32 v2, 12, v2
	v_lshl_add_u64 v[34:35], v[16:17], 0, v[2:3]
	global_store_dwordx4 v[34:35], v[30:33], off
	ds_read2_b32 v[34:35], v26 offset0:49 offset1:57
	ds_read2_b32 v[36:37], v26 offset0:16 offset1:24
	ds_read2_b32 v[38:39], v26 offset0:82 offset1:90
	ds_read2_b32 v[40:41], v26 offset0:115 offset1:123
	ds_read2_b32 v[42:43], v26 offset0:148 offset1:156
	ds_read2_b32 v[44:45], v26 offset0:181 offset1:189
	ds_read2_b32 v[46:47], v26 offset0:214 offset1:222
	ds_read2_b32 v[48:49], v26 offset0:247 offset1:255
	s_waitcnt lgkmcnt(7)
	s_waitcnt lgkmcnt(6)
	v_cvt_pk_bf16_f32 v30, v36, v34
	s_waitcnt lgkmcnt(5)
	s_waitcnt lgkmcnt(4)
	v_cvt_pk_bf16_f32 v31, v38, v40
	s_waitcnt lgkmcnt(3)
	s_waitcnt lgkmcnt(2)
	v_cvt_pk_bf16_f32 v32, v42, v44
	s_waitcnt lgkmcnt(1)
	s_waitcnt lgkmcnt(0)
	v_cvt_pk_bf16_f32 v33, v46, v48
	v_or_b32_e32 v2, s16, v24
	v_lshlrev_b32_e32 v2, 12, v2
	v_lshl_add_u64 v[50:51], v[16:17], 0, v[2:3]
	global_store_dwordx4 v[50:51], v[30:33], off
	s_nop 1
	v_cvt_pk_bf16_f32 v30, v37, v35
	v_cvt_pk_bf16_f32 v31, v39, v41
	v_cvt_pk_bf16_f32 v32, v43, v45
	v_cvt_pk_bf16_f32 v33, v47, v49
	v_or_b32_e32 v2, s16, v25
	v_lshlrev_b32_e32 v2, 12, v2
	v_lshl_add_u64 v[16:17], v[16:17], 0, v[2:3]
	global_store_dwordx4 v[16:17], v[30:33], off
	s_waitcnt lgkmcnt(0)

.LBB0_1058:
	s_andn2_b64 vcc, exec, s[16:17]
	s_cbranch_vccnz .LBB0_1060
	s_and_b32 s16, s6, 0x7e0
	s_add_i32 s8, s7, 0xcc00
	v_or_b32_e32 v2, s16, v19
	s_and_b32 s8, s8, 0xffc0
	v_or_b32_e32 v29, s8, v20
	v_lshlrev_b32_e32 v2, 2, v2
	v_lshl_add_u64 v[16:17], s[40:41], 0, v[2:3]
	v_lshlrev_b32_e32 v2, 13, v29
	v_lshl_add_u64 v[16:17], v[16:17], 0, v[2:3]
	v_add_co_u32_e32 v34, vcc, 0x10000, v16
	global_load_dwordx4 v[30:33], v[16:17], off
	s_nop 0
	v_addc_co_u32_e32 v35, vcc, 0, v17, vcc
	global_load_dwordx4 v[34:37], v[34:35], off
	v_add_co_u32_e32 v38, vcc, 0x20000, v16
	v_add_u32_e32 v2, v21, v22
	s_nop 0
	v_addc_co_u32_e32 v39, vcc, 0, v17, vcc
	global_load_dwordx4 v[38:41], v[38:39], off
	v_add_co_u32_e32 v42, vcc, 0x30000, v16
	s_lshl_b32 s36, s8, 1
	s_nop 0
	v_addc_co_u32_e32 v43, vcc, 0, v17, vcc
	global_load_dwordx4 v[42:45], v[42:43], off
	v_add_co_u32_e32 v46, vcc, 0x40000, v16
	s_nop 1
	v_addc_co_u32_e32 v47, vcc, 0, v17, vcc
	global_load_dwordx4 v[46:49], v[46:47], off
	v_add_co_u32_e32 v50, vcc, 0x50000, v16
	s_nop 1
	v_addc_co_u32_e32 v51, vcc, 0, v17, vcc
	global_load_dwordx4 v[50:53], v[50:51], off
	v_add_co_u32_e32 v54, vcc, 0x60000, v16
	s_nop 1
	v_addc_co_u32_e32 v55, vcc, 0, v17, vcc
	global_load_dwordx4 v[54:57], v[54:55], off
	v_add_co_u32_e32 v16, vcc, 0x70000, v16
	s_nop 1
	v_addc_co_u32_e32 v17, vcc, 0, v17, vcc
	global_load_dwordx4 v[58:61], v[16:17], off
	v_add_u32_e32 v16, 0x420, v2
	s_waitcnt vmcnt(0)
	ds_write2_b32 v2, v30, v31 offset1:1
	ds_write2_b32 v2, v32, v33 offset0:2 offset1:3
	ds_write2_b32 v16, v34, v35 offset1:1
	v_add_u32_e32 v16, 0x428, v2
	ds_write2_b32 v16, v36, v37 offset1:1
	v_add_u32_e32 v16, 0x840, v2
	ds_write2_b32 v16, v38, v39 offset1:1
	v_add_u32_e32 v16, 0x848, v2
	ds_write2_b32 v16, v40, v41 offset1:1
	v_add_u32_e32 v16, 0xc60, v2
	ds_write2_b32 v16, v42, v43 offset1:1
	v_add_u32_e32 v16, 0xc68, v2
	ds_write2_b32 v16, v44, v45 offset1:1
	v_add_u32_e32 v16, 0x1080, v2
	ds_write2_b32 v16, v46, v47 offset1:1
	v_add_u32_e32 v16, 0x1088, v2
	ds_write2_b32 v16, v48, v49 offset1:1
	v_add_u32_e32 v16, 0x14a0, v2
	ds_write2_b32 v16, v50, v51 offset1:1
	v_add_u32_e32 v16, 0x14a8, v2
	ds_write2_b32 v16, v52, v53 offset1:1
	v_add_u32_e32 v16, 0x18c0, v2
	ds_write2_b32 v16, v54, v55 offset1:1
	v_add_u32_e32 v16, 0x18c8, v2
	ds_write2_b32 v16, v56, v57 offset1:1
	v_add_u32_e32 v16, 0x1ce0, v2
	v_add_u32_e32 v2, 0x1ce8, v2
	ds_write2_b32 v16, v58, v59 offset1:1
	ds_write2_b32 v2, v60, v61 offset1:1
	s_waitcnt lgkmcnt(0)
	ds_read2_b32 v[34:35], v26 offset0:33 offset1:41
	ds_read2_b32 v[36:37], v26 offset1:8
	ds_read2_b32 v[38:39], v26 offset0:66 offset1:74
	ds_read2_b32 v[40:41], v26 offset0:99 offset1:107
	ds_read2_b32 v[42:43], v26 offset0:132 offset1:140
	ds_read2_b32 v[44:45], v26 offset0:165 offset1:173
	ds_read2_b32 v[46:47], v26 offset0:198 offset1:206
	ds_read2_b32 v[48:49], v26 offset0:231 offset1:239
	s_waitcnt lgkmcnt(0)
	v_cvt_pk_bf16_f32 v30, v36, v34
	v_cvt_pk_bf16_f32 v31, v38, v40
	v_cvt_pk_bf16_f32 v32, v42, v44
	v_cvt_pk_bf16_f32 v33, v46, v48
	v_or_b32_e32 v2, s16, v20
	v_lshl_add_u64 v[16:17], v[10:11], 0, s[36:37]
	v_lshlrev_b32_e32 v2, 12, v2
	v_lshl_add_u64 v[50:51], v[16:17], 0, v[2:3]
	global_store_dwordx4 v[50:51], v[30:33], off
	s_nop 1
	v_cvt_pk_bf16_f32 v30, v37, v35
	v_cvt_pk_bf16_f32 v31, v39, v41
	v_cvt_pk_bf16_f32 v32, v43, v45
	v_cvt_pk_bf16_f32 v33, v47, v49
	v_or_b32_e32 v2, s16, v23
	v_lshlrev_b32_e32 v2, 12, v2
	v_lshl_add_u64 v[34:35], v[16:17], 0, v[2:3]
	global_store_dwordx4 v[34:35], v[30:33], off
	ds_read2_b32 v[34:35], v26 offset0:49 offset1:57
	ds_read2_b32 v[36:37], v26 offset0:16 offset1:24
	ds_read2_b32 v[38:39], v26 offset0:82 offset1:90
	ds_read2_b32 v[40:41], v26 offset0:115 offset1:123
	ds_read2_b32 v[42:43], v26 offset0:148 offset1:156
	ds_read2_b32 v[44:45], v26 offset0:181 offset1:189
	ds_read2_b32 v[46:47], v26 offset0:214 offset1:222
	ds_read2_b32 v[48:49], v26 offset0:247 offset1:255
	s_waitcnt lgkmcnt(7)
	s_waitcnt lgkmcnt(6)
	v_cvt_pk_bf16_f32 v30, v36, v34
	s_waitcnt lgkmcnt(5)
	s_waitcnt lgkmcnt(4)
	v_cvt_pk_bf16_f32 v31, v38, v40
	s_waitcnt lgkmcnt(3)
	s_waitcnt lgkmcnt(2)
	v_cvt_pk_bf16_f32 v32, v42, v44
	s_waitcnt lgkmcnt(1)
	s_waitcnt lgkmcnt(0)
	v_cvt_pk_bf16_f32 v33, v46, v48
	v_or_b32_e32 v2, s16, v24
	v_lshlrev_b32_e32 v2, 12, v2
	v_lshl_add_u64 v[50:51], v[16:17], 0, v[2:3]
	global_store_dwordx4 v[50:51], v[30:33], off
	s_nop 1
	v_cvt_pk_bf16_f32 v30, v37, v35
	v_cvt_pk_bf16_f32 v31, v39, v41
	v_cvt_pk_bf16_f32 v32, v43, v45
	v_cvt_pk_bf16_f32 v33, v47, v49
	v_or_b32_e32 v2, s16, v25
	v_lshlrev_b32_e32 v2, 12, v2
	v_lshl_add_u64 v[16:17], v[16:17], 0, v[2:3]
	global_store_dwordx4 v[16:17], v[30:33], off
	s_waitcnt lgkmcnt(0)

.LBB0_1061:
	s_andn2_b64 vcc, exec, s[16:17]
	s_cbranch_vccnz .LBB0_1063
	s_and_b32 s16, s6, 0x7e0
	s_add_i32 s8, s7, 0xd400
	v_or_b32_e32 v2, s16, v19
	s_and_b32 s8, s8, 0xffc0
	v_or_b32_e32 v29, s8, v20
	v_lshlrev_b32_e32 v2, 2, v2
	v_lshl_add_u64 v[16:17], s[42:43], 0, v[2:3]
	v_lshlrev_b32_e32 v2, 13, v29
	v_lshl_add_u64 v[16:17], v[16:17], 0, v[2:3]
	v_add_co_u32_e32 v34, vcc, 0x10000, v16
	global_load_dwordx4 v[30:33], v[16:17], off
	s_nop 0
	v_addc_co_u32_e32 v35, vcc, 0, v17, vcc
	global_load_dwordx4 v[34:37], v[34:35], off
	v_add_co_u32_e32 v38, vcc, 0x20000, v16
	v_add_u32_e32 v2, v21, v22
	s_nop 0
	v_addc_co_u32_e32 v39, vcc, 0, v17, vcc
	global_load_dwordx4 v[38:41], v[38:39], off
	v_add_co_u32_e32 v42, vcc, 0x30000, v16
	s_lshl_b32 s36, s8, 1
	s_nop 0
	v_addc_co_u32_e32 v43, vcc, 0, v17, vcc
	global_load_dwordx4 v[42:45], v[42:43], off
	v_add_co_u32_e32 v46, vcc, 0x40000, v16
	s_nop 1
	v_addc_co_u32_e32 v47, vcc, 0, v17, vcc
	global_load_dwordx4 v[46:49], v[46:47], off
	v_add_co_u32_e32 v50, vcc, 0x50000, v16
	s_nop 1
	v_addc_co_u32_e32 v51, vcc, 0, v17, vcc
	global_load_dwordx4 v[50:53], v[50:51], off
	v_add_co_u32_e32 v54, vcc, 0x60000, v16
	s_nop 1
	v_addc_co_u32_e32 v55, vcc, 0, v17, vcc
	global_load_dwordx4 v[54:57], v[54:55], off
	v_add_co_u32_e32 v16, vcc, 0x70000, v16
	s_nop 1
	v_addc_co_u32_e32 v17, vcc, 0, v17, vcc
	global_load_dwordx4 v[58:61], v[16:17], off
	v_add_u32_e32 v16, 0x420, v2
	s_waitcnt vmcnt(0)
	ds_write2_b32 v2, v30, v31 offset1:1
	ds_write2_b32 v2, v32, v33 offset0:2 offset1:3
	ds_write2_b32 v16, v34, v35 offset1:1
	v_add_u32_e32 v16, 0x428, v2
	ds_write2_b32 v16, v36, v37 offset1:1
	v_add_u32_e32 v16, 0x840, v2
	ds_write2_b32 v16, v38, v39 offset1:1
	v_add_u32_e32 v16, 0x848, v2
	ds_write2_b32 v16, v40, v41 offset1:1
	v_add_u32_e32 v16, 0xc60, v2
	ds_write2_b32 v16, v42, v43 offset1:1
	v_add_u32_e32 v16, 0xc68, v2
	ds_write2_b32 v16, v44, v45 offset1:1
	v_add_u32_e32 v16, 0x1080, v2
	ds_write2_b32 v16, v46, v47 offset1:1
	v_add_u32_e32 v16, 0x1088, v2
	ds_write2_b32 v16, v48, v49 offset1:1
	v_add_u32_e32 v16, 0x14a0, v2
	ds_write2_b32 v16, v50, v51 offset1:1
	v_add_u32_e32 v16, 0x14a8, v2
	ds_write2_b32 v16, v52, v53 offset1:1
	v_add_u32_e32 v16, 0x18c0, v2
	ds_write2_b32 v16, v54, v55 offset1:1
	v_add_u32_e32 v16, 0x18c8, v2
	ds_write2_b32 v16, v56, v57 offset1:1
	v_add_u32_e32 v16, 0x1ce0, v2
	v_add_u32_e32 v2, 0x1ce8, v2
	ds_write2_b32 v16, v58, v59 offset1:1
	ds_write2_b32 v2, v60, v61 offset1:1
	s_waitcnt lgkmcnt(0)
	ds_read2_b32 v[34:35], v26 offset0:33 offset1:41
	ds_read2_b32 v[36:37], v26 offset1:8
	ds_read2_b32 v[38:39], v26 offset0:66 offset1:74
	ds_read2_b32 v[40:41], v26 offset0:99 offset1:107
	ds_read2_b32 v[42:43], v26 offset0:132 offset1:140
	ds_read2_b32 v[44:45], v26 offset0:165 offset1:173
	ds_read2_b32 v[46:47], v26 offset0:198 offset1:206
	ds_read2_b32 v[48:49], v26 offset0:231 offset1:239
	s_waitcnt lgkmcnt(0)
	v_cvt_pk_bf16_f32 v30, v36, v34
	v_cvt_pk_bf16_f32 v31, v38, v40
	v_cvt_pk_bf16_f32 v32, v42, v44
	v_cvt_pk_bf16_f32 v33, v46, v48
	v_or_b32_e32 v2, s16, v20
	v_lshl_add_u64 v[16:17], v[12:13], 0, s[36:37]
	v_lshlrev_b32_e32 v2, 12, v2
	v_lshl_add_u64 v[50:51], v[16:17], 0, v[2:3]
	global_store_dwordx4 v[50:51], v[30:33], off
	s_nop 1
	v_cvt_pk_bf16_f32 v30, v37, v35
	v_cvt_pk_bf16_f32 v31, v39, v41
	v_cvt_pk_bf16_f32 v32, v43, v45
	v_cvt_pk_bf16_f32 v33, v47, v49
	v_or_b32_e32 v2, s16, v23
	v_lshlrev_b32_e32 v2, 12, v2
	v_lshl_add_u64 v[34:35], v[16:17], 0, v[2:3]
	global_store_dwordx4 v[34:35], v[30:33], off
	ds_read2_b32 v[34:35], v26 offset0:49 offset1:57
	ds_read2_b32 v[36:37], v26 offset0:16 offset1:24
	ds_read2_b32 v[38:39], v26 offset0:82 offset1:90
	ds_read2_b32 v[40:41], v26 offset0:115 offset1:123
	ds_read2_b32 v[42:43], v26 offset0:148 offset1:156
	ds_read2_b32 v[44:45], v26 offset0:181 offset1:189
	ds_read2_b32 v[46:47], v26 offset0:214 offset1:222
	ds_read2_b32 v[48:49], v26 offset0:247 offset1:255
	s_waitcnt lgkmcnt(7)
	s_waitcnt lgkmcnt(6)
	v_cvt_pk_bf16_f32 v30, v36, v34
	s_waitcnt lgkmcnt(5)
	s_waitcnt lgkmcnt(4)
	v_cvt_pk_bf16_f32 v31, v38, v40
	s_waitcnt lgkmcnt(3)
	s_waitcnt lgkmcnt(2)
	v_cvt_pk_bf16_f32 v32, v42, v44
	s_waitcnt lgkmcnt(1)
	s_waitcnt lgkmcnt(0)
	v_cvt_pk_bf16_f32 v33, v46, v48
	v_or_b32_e32 v2, s16, v24
	v_lshlrev_b32_e32 v2, 12, v2
	v_lshl_add_u64 v[50:51], v[16:17], 0, v[2:3]
	global_store_dwordx4 v[50:51], v[30:33], off
	s_nop 1
	v_cvt_pk_bf16_f32 v30, v37, v35
	v_cvt_pk_bf16_f32 v31, v39, v41
	v_cvt_pk_bf16_f32 v32, v43, v45
	v_cvt_pk_bf16_f32 v33, v47, v49
	v_or_b32_e32 v2, s16, v25
	v_lshlrev_b32_e32 v2, 12, v2
	v_lshl_add_u64 v[16:17], v[16:17], 0, v[2:3]
	global_store_dwordx4 v[16:17], v[30:33], off
	s_waitcnt lgkmcnt(0)

.LBB0_1064:
	s_andn2_b64 vcc, exec, s[16:17]
	s_cbranch_vccnz .LBB0_1066
	s_and_b32 s16, s6, 0x7e0
	s_add_i32 s8, s7, 0xd800
	v_or_b32_e32 v2, s16, v19
	s_and_b32 s8, s8, 0xffc0
	v_or_b32_e32 v29, s8, v20
	v_lshlrev_b32_e32 v2, 2, v2
	v_lshl_add_u64 v[16:17], s[48:49], 0, v[2:3]
	v_lshlrev_b32_e32 v2, 13, v29
	v_lshl_add_u64 v[16:17], v[16:17], 0, v[2:3]
	v_add_co_u32_e32 v34, vcc, 0x10000, v16
	global_load_dwordx4 v[30:33], v[16:17], off
	s_nop 0
	v_addc_co_u32_e32 v35, vcc, 0, v17, vcc
	global_load_dwordx4 v[34:37], v[34:35], off
	v_add_co_u32_e32 v38, vcc, 0x20000, v16
	v_add_u32_e32 v2, v21, v22
	s_nop 0
	v_addc_co_u32_e32 v39, vcc, 0, v17, vcc
	global_load_dwordx4 v[38:41], v[38:39], off
	v_add_co_u32_e32 v42, vcc, 0x30000, v16
	s_lshl_b32 s36, s8, 1
	s_nop 0
	v_addc_co_u32_e32 v43, vcc, 0, v17, vcc
	global_load_dwordx4 v[42:45], v[42:43], off
	v_add_co_u32_e32 v46, vcc, 0x40000, v16
	s_nop 1
	v_addc_co_u32_e32 v47, vcc, 0, v17, vcc
	global_load_dwordx4 v[46:49], v[46:47], off
	v_add_co_u32_e32 v50, vcc, 0x50000, v16
	s_nop 1
	v_addc_co_u32_e32 v51, vcc, 0, v17, vcc
	global_load_dwordx4 v[50:53], v[50:51], off
	v_add_co_u32_e32 v54, vcc, 0x60000, v16
	s_nop 1
	v_addc_co_u32_e32 v55, vcc, 0, v17, vcc
	global_load_dwordx4 v[54:57], v[54:55], off
	v_add_co_u32_e32 v16, vcc, 0x70000, v16
	s_nop 1
	v_addc_co_u32_e32 v17, vcc, 0, v17, vcc
	global_load_dwordx4 v[58:61], v[16:17], off
	v_add_u32_e32 v16, 0x420, v2
	s_waitcnt vmcnt(0)
	ds_write2_b32 v2, v30, v31 offset1:1
	ds_write2_b32 v2, v32, v33 offset0:2 offset1:3
	ds_write2_b32 v16, v34, v35 offset1:1
	v_add_u32_e32 v16, 0x428, v2
	ds_write2_b32 v16, v36, v37 offset1:1
	v_add_u32_e32 v16, 0x840, v2
	ds_write2_b32 v16, v38, v39 offset1:1
	v_add_u32_e32 v16, 0x848, v2
	ds_write2_b32 v16, v40, v41 offset1:1
	v_add_u32_e32 v16, 0xc60, v2
	ds_write2_b32 v16, v42, v43 offset1:1
	v_add_u32_e32 v16, 0xc68, v2
	ds_write2_b32 v16, v44, v45 offset1:1
	v_add_u32_e32 v16, 0x1080, v2
	ds_write2_b32 v16, v46, v47 offset1:1
	v_add_u32_e32 v16, 0x1088, v2
	ds_write2_b32 v16, v48, v49 offset1:1
	v_add_u32_e32 v16, 0x14a0, v2
	ds_write2_b32 v16, v50, v51 offset1:1
	v_add_u32_e32 v16, 0x14a8, v2
	ds_write2_b32 v16, v52, v53 offset1:1
	v_add_u32_e32 v16, 0x18c0, v2
	ds_write2_b32 v16, v54, v55 offset1:1
	v_add_u32_e32 v16, 0x18c8, v2
	ds_write2_b32 v16, v56, v57 offset1:1
	v_add_u32_e32 v16, 0x1ce0, v2
	v_add_u32_e32 v2, 0x1ce8, v2
	ds_write2_b32 v16, v58, v59 offset1:1
	ds_write2_b32 v2, v60, v61 offset1:1
	s_waitcnt lgkmcnt(0)
	ds_read2_b32 v[34:35], v26 offset0:33 offset1:41
	ds_read2_b32 v[36:37], v26 offset1:8
	ds_read2_b32 v[38:39], v26 offset0:66 offset1:74
	ds_read2_b32 v[40:41], v26 offset0:99 offset1:107
	ds_read2_b32 v[42:43], v26 offset0:132 offset1:140
	ds_read2_b32 v[44:45], v26 offset0:165 offset1:173
	ds_read2_b32 v[46:47], v26 offset0:198 offset1:206
	ds_read2_b32 v[48:49], v26 offset0:231 offset1:239
	s_waitcnt lgkmcnt(0)
	v_cvt_pk_bf16_f32 v30, v36, v34
	v_cvt_pk_bf16_f32 v31, v38, v40
	v_cvt_pk_bf16_f32 v32, v42, v44
	v_cvt_pk_bf16_f32 v33, v46, v48
	v_or_b32_e32 v2, s16, v20
	v_lshl_add_u64 v[16:17], v[14:15], 0, s[36:37]
	v_lshlrev_b32_e32 v2, 12, v2
	v_lshl_add_u64 v[50:51], v[16:17], 0, v[2:3]
	global_store_dwordx4 v[50:51], v[30:33], off
	s_nop 1
	v_cvt_pk_bf16_f32 v30, v37, v35
	v_cvt_pk_bf16_f32 v31, v39, v41
	v_cvt_pk_bf16_f32 v32, v43, v45
	v_cvt_pk_bf16_f32 v33, v47, v49
	v_or_b32_e32 v2, s16, v23
	v_lshlrev_b32_e32 v2, 12, v2
	v_lshl_add_u64 v[34:35], v[16:17], 0, v[2:3]
	global_store_dwordx4 v[34:35], v[30:33], off
	ds_read2_b32 v[34:35], v26 offset0:49 offset1:57
	ds_read2_b32 v[36:37], v26 offset0:16 offset1:24
	ds_read2_b32 v[38:39], v26 offset0:82 offset1:90
	ds_read2_b32 v[40:41], v26 offset0:115 offset1:123
	ds_read2_b32 v[42:43], v26 offset0:148 offset1:156
	ds_read2_b32 v[44:45], v26 offset0:181 offset1:189
	ds_read2_b32 v[46:47], v26 offset0:214 offset1:222
	ds_read2_b32 v[48:49], v26 offset0:247 offset1:255
	s_waitcnt lgkmcnt(7)
	s_waitcnt lgkmcnt(6)
	v_cvt_pk_bf16_f32 v30, v36, v34
	s_waitcnt lgkmcnt(5)
	s_waitcnt lgkmcnt(4)
	v_cvt_pk_bf16_f32 v31, v38, v40
	s_waitcnt lgkmcnt(3)
	s_waitcnt lgkmcnt(2)
	v_cvt_pk_bf16_f32 v32, v42, v44
	s_waitcnt lgkmcnt(1)
	s_waitcnt lgkmcnt(0)
	v_cvt_pk_bf16_f32 v33, v46, v48
	v_or_b32_e32 v2, s16, v24
	v_lshlrev_b32_e32 v2, 12, v2
	v_lshl_add_u64 v[50:51], v[16:17], 0, v[2:3]
	global_store_dwordx4 v[50:51], v[30:33], off
	s_nop 1
	v_cvt_pk_bf16_f32 v30, v37, v35
	v_cvt_pk_bf16_f32 v31, v39, v41
	v_cvt_pk_bf16_f32 v32, v43, v45
	v_cvt_pk_bf16_f32 v33, v47, v49
	v_or_b32_e32 v2, s16, v25
	v_lshlrev_b32_e32 v2, 12, v2
	v_lshl_add_u64 v[16:17], v[16:17], 0, v[2:3]
	global_store_dwordx4 v[16:17], v[30:33], off
	s_waitcnt lgkmcnt(0)
